# mix_state GLA gate pre-activations (columns 8-47) on the f32 matrix cores (v_mfma_f32_32x32x2_f32, operands from LDS-staged weights) instead of 16-term VALU FMA chains
# baseline (speedup 1.0000x reference)
.LBB0_659:
	s_or_b64 exec, exec, s[0:1]
	v_readlane_b32 s0, v254, 43
	v_readlane_b32 s1, v254, 44
	v_lshrrev_b32_e32 v123, 6, v198
	v_and_b32_e32 v124, 1, v123
	v_lshrrev_b32_e32 v123, 1, v123
	v_mul_u32_u24_e32 v124, 0x3000, v124
	v_lshl_add_u32 v124, v123, 7, v124
	v_lshl_add_u32 v123, v123, 6, v124
	v_add_u32_e32 v123, 0x1b000, v123
	v_bfe_u32 v124, v198, 5, 1
	v_and_b32_e32 v125, 31, v198
	v_mul_u32_u24_e32 v126, 0x300, v124
	v_lshl_add_u32 v126, v125, 2, v126
	v_add_u32_e32 v126, v126, v123
	v_lshl_add_u32 v125, v124, 4, v123
	v_mov_b32_e32 v107, v242
	v_mov_b32_e32 v108, v223
	v_mov_b32_e32 v109, v222
	v_mov_b32_e32 v110, v221
	v_mov_b32_e32 v111, v220
	v_mov_b32_e32 v112, v219
	v_mov_b32_e32 v113, v218
	v_mov_b32_e32 v114, v217
	v_mov_b32_e32 v115, v216
	v_mov_b32_e32 v116, v215
	v_mov_b32_e32 v117, v214
	v_mov_b32_e32 v118, v213
	v_mov_b32_e32 v119, v206
	v_mov_b32_e32 v120, v207
	v_mov_b32_e32 v121, v204
	v_mov_b32_e32 v122, v205
	s_nop 1
	v_permlane32_swap_b32 v107, v108
	v_permlane32_swap_b32 v109, v110
	v_permlane32_swap_b32 v111, v112
	v_permlane32_swap_b32 v113, v114
	v_permlane32_swap_b32 v115, v116
	v_permlane32_swap_b32 v117, v118
	v_permlane32_swap_b32 v119, v120
	v_permlane32_swap_b32 v121, v122
	ds_read_b32 v59, v126 offset:0
	ds_read_b32 v93, v126 offset:1536
	ds_read_b32 v95, v126 offset:3072
	ds_read_b32 v97, v126 offset:4608
	ds_read_b32 v99, v126 offset:6144
	ds_read_b32 v101, v126 offset:7680
	ds_read_b32 v103, v126 offset:9216
	ds_read_b32 v105, v126 offset:10752
	s_waitcnt lgkmcnt(0)
	ds_read_b128 v[60:63], v125 offset:24576
	ds_read_b128 v[64:67], v125 offset:24608
	ds_read_b128 v[68:71], v125 offset:24640
	ds_read_b128 v[72:75], v125 offset:24672
	ds_read_b128 v[76:79], v125 offset:24576
	ds_read_b128 v[80:83], v125 offset:24608
	ds_read_b128 v[84:87], v125 offset:24640
	ds_read_b128 v[88:91], v125 offset:24672
	s_waitcnt lgkmcnt(0)
	s_nop 3
	v_mfma_f32_32x32x2_f32 v[60:75], v59, v107, v[60:75]
	v_mfma_f32_32x32x2_f32 v[76:91], v59, v108, v[76:91]
	v_mfma_f32_32x32x2_f32 v[60:75], v93, v109, v[60:75]
	v_mfma_f32_32x32x2_f32 v[76:91], v93, v110, v[76:91]
	v_mfma_f32_32x32x2_f32 v[60:75], v95, v111, v[60:75]
	v_mfma_f32_32x32x2_f32 v[76:91], v95, v112, v[76:91]
	v_mfma_f32_32x32x2_f32 v[60:75], v97, v113, v[60:75]
	v_mfma_f32_32x32x2_f32 v[76:91], v97, v114, v[76:91]
	v_mfma_f32_32x32x2_f32 v[60:75], v99, v115, v[60:75]
	v_mfma_f32_32x32x2_f32 v[76:91], v99, v116, v[76:91]
	v_mfma_f32_32x32x2_f32 v[60:75], v101, v117, v[60:75]
	v_mfma_f32_32x32x2_f32 v[76:91], v101, v118, v[76:91]
	v_mfma_f32_32x32x2_f32 v[60:75], v103, v119, v[60:75]
	v_mfma_f32_32x32x2_f32 v[76:91], v103, v120, v[76:91]
	v_mfma_f32_32x32x2_f32 v[60:75], v105, v121, v[60:75]
	v_mfma_f32_32x32x2_f32 v[76:91], v105, v122, v[76:91]
	s_nop 15
	s_nop 7
	v_permlane32_swap_b32 v64, v80
	v_permlane32_swap_b32 v65, v81
	v_permlane32_swap_b32 v66, v82
	v_permlane32_swap_b32 v67, v83
	v_permlane32_swap_b32 v68, v84
	v_permlane32_swap_b32 v69, v85
	v_permlane32_swap_b32 v70, v86
	v_permlane32_swap_b32 v71, v87
	v_permlane32_swap_b32 v72, v88
	v_permlane32_swap_b32 v73, v89
	v_permlane32_swap_b32 v74, v90
	v_permlane32_swap_b32 v75, v91
	v_mov_b32_e32 v131, v64
	v_mov_b32_e32 v132, v65
	v_mov_b32_e32 v133, v66
	v_mov_b32_e32 v134, v67
	v_mov_b32_e32 v135, v80
	v_mov_b32_e32 v136, v81
	v_mov_b32_e32 v137, v82
	v_mov_b32_e32 v138, v83
	v_mov_b32_e32 v139, v68
	v_mov_b32_e32 v140, v69
	v_mov_b32_e32 v141, v70
	v_mov_b32_e32 v142, v71
	v_mov_b32_e32 v143, v84
	v_mov_b32_e32 v144, v85
	v_mov_b32_e32 v145, v86
	v_mov_b32_e32 v146, v87
	v_mov_b32_e32 v148, v72
	v_mov_b32_e32 v149, v73
	v_mov_b32_e32 v150, v74
	v_mov_b32_e32 v151, v75
	v_mov_b32_e32 v152, v88
	v_mov_b32_e32 v153, v89
	v_mov_b32_e32 v154, v90
	v_mov_b32_e32 v155, v91
	s_nop 1
	ds_read_b32 v92, v126 offset:128
	ds_read_b32 v94, v126 offset:1664
	ds_read_b32 v96, v126 offset:3200
	ds_read_b32 v98, v126 offset:4736
	ds_read_b32 v100, v126 offset:6272
	ds_read_b32 v102, v126 offset:7808
	ds_read_b32 v104, v126 offset:9344
	ds_read_b32 v106, v126 offset:10880
	s_waitcnt lgkmcnt(0)
	ds_read_b128 v[60:63], v125 offset:24704
	ds_read_b128 v[64:67], v125 offset:24736
	ds_read_b128 v[68:71], v125 offset:24768
	ds_read_b128 v[72:75], v125 offset:24800
	ds_read_b128 v[76:79], v125 offset:24704
	ds_read_b128 v[80:83], v125 offset:24736
	ds_read_b128 v[84:87], v125 offset:24768
	ds_read_b128 v[88:91], v125 offset:24800
	s_waitcnt lgkmcnt(0)
	s_nop 3
	v_mfma_f32_32x32x2_f32 v[60:75], v92, v107, v[60:75]
	v_mfma_f32_32x32x2_f32 v[76:91], v92, v108, v[76:91]
	v_mfma_f32_32x32x2_f32 v[60:75], v94, v109, v[60:75]
	v_mfma_f32_32x32x2_f32 v[76:91], v94, v110, v[76:91]
	v_mfma_f32_32x32x2_f32 v[60:75], v96, v111, v[60:75]
	v_mfma_f32_32x32x2_f32 v[76:91], v96, v112, v[76:91]
	v_mfma_f32_32x32x2_f32 v[60:75], v98, v113, v[60:75]
	v_mfma_f32_32x32x2_f32 v[76:91], v98, v114, v[76:91]
	v_mfma_f32_32x32x2_f32 v[60:75], v100, v115, v[60:75]
	v_mfma_f32_32x32x2_f32 v[76:91], v100, v116, v[76:91]
	v_mfma_f32_32x32x2_f32 v[60:75], v102, v117, v[60:75]
	v_mfma_f32_32x32x2_f32 v[76:91], v102, v118, v[76:91]
	v_mfma_f32_32x32x2_f32 v[60:75], v104, v119, v[60:75]
	v_mfma_f32_32x32x2_f32 v[76:91], v104, v120, v[76:91]
	v_mfma_f32_32x32x2_f32 v[60:75], v106, v121, v[60:75]
	v_mfma_f32_32x32x2_f32 v[76:91], v106, v122, v[76:91]
	s_nop 15
	s_nop 7
	v_permlane32_swap_b32 v60, v76
	v_permlane32_swap_b32 v61, v77
	v_permlane32_swap_b32 v62, v78
	v_permlane32_swap_b32 v63, v79
	v_permlane32_swap_b32 v64, v80
	v_permlane32_swap_b32 v65, v81
	v_permlane32_swap_b32 v66, v82
	v_permlane32_swap_b32 v67, v83
	v_mov_b32_e32 v156, v60
	v_mov_b32_e32 v164, v61
	v_mov_b32_e32 v165, v62
	v_mov_b32_e32 v166, v63
	v_mov_b32_e32 v167, v76
	v_mov_b32_e32 v168, v77
	v_mov_b32_e32 v169, v78
	v_mov_b32_e32 v170, v79
	v_mov_b32_e32 v171, v64
	v_mov_b32_e32 v176, v65
	v_mov_b32_e32 v177, v66
	v_mov_b32_e32 v178, v67
	v_mov_b32_e32 v179, v80
	v_mov_b32_e32 v180, v81
	v_mov_b32_e32 v181, v82
	v_mov_b32_e32 v184, v83
	s_nop 15
	s_nop 2
	s_waitcnt lgkmcnt(8)
	s_nop 3
	s_waitcnt lgkmcnt(8)
	v_readlane_b32 s0, v254, 45
	v_readlane_b32 s1, v254, 46
	s_nop 4
	s_nop 1
	v_readlane_b32 s0, v254, 47
	v_readlane_b32 s1, v254, 48
	s_nop 4
	s_nop 1
	s_waitcnt lgkmcnt(8)
	v_readlane_b32 s0, v254, 49
	v_readlane_b32 s1, v254, 50
	s_nop 4
	s_nop 1
	v_readlane_b32 s0, v254, 51
	v_readlane_b32 s1, v254, 52
	s_nop 4
	s_nop 1
	s_waitcnt lgkmcnt(8)
	v_readlane_b32 s0, v254, 53
	v_readlane_b32 s1, v254, 54
	s_nop 4
	s_nop 1
	v_readlane_b32 s0, v254, 55
	v_readlane_b32 s1, v254, 56
	s_nop 4
	s_nop 1
	s_waitcnt lgkmcnt(8)
	v_readlane_b32 s0, v254, 57
	v_readlane_b32 s1, v254, 58
	s_nop 4
	s_nop 1
	v_readlane_b32 s0, v254, 59
	v_readlane_b32 s1, v254, 60
	s_waitcnt lgkmcnt(14)
	s_nop 0
	s_waitcnt lgkmcnt(14)
	s_nop 0
	s_waitcnt lgkmcnt(14)
	s_nop 0
	s_waitcnt lgkmcnt(14)
	s_nop 0
	s_waitcnt lgkmcnt(14)
	s_nop 0
	s_waitcnt lgkmcnt(14)
	s_nop 0
	s_waitcnt lgkmcnt(14)
	s_nop 0
	s_waitcnt lgkmcnt(14)
	s_nop 2
	s_waitcnt lgkmcnt(12)
	s_nop 2
	s_waitcnt lgkmcnt(10)
	s_nop 2
	s_waitcnt lgkmcnt(8)
	s_nop 2
	s_waitcnt lgkmcnt(6)
	s_nop 2
	s_waitcnt lgkmcnt(4)
	s_nop 2
	s_waitcnt lgkmcnt(2)
	s_nop 2
	s_waitcnt lgkmcnt(0)
	s_nop 13
	v_readlane_b32 s0, v254, 61
	v_readlane_b32 s1, v254, 62
	s_nop 4
	s_nop 15
	s_nop 15
	s_nop 14
	v_lshlrev_b32_e32 v64, 16, v36
	v_and_b32_e32 v65, 0xffff0000, v36
	v_and_b32_e32 v67, 0xffff0000, v37
	v_lshlrev_b32_e32 v68, 16, v38
	v_and_b32_e32 v69, 0xffff0000, v38
	v_lshlrev_b32_e32 v70, 16, v39
	v_and_b32_e32 v71, 0xffff0000, v39
	s_waitcnt lgkmcnt(2)
	s_nop 0
	s_waitcnt lgkmcnt(0)
	s_nop 4
	v_mov_b32_e32 v48, v131
	v_max_f32_e64 v126, -v48, 0
	v_mul_f32_e64 v48, |v48|, s93
	v_exp_f32_e32 v48, v48
	s_nop 0
	v_add_f32_e32 v48, 1.0, v48
	s_nop 0
	s_nop 1
	s_nop 0
	s_nop 0
	v_log_f32_e32 v48, v48
	s_nop 0
	v_mul_f32_e32 v130, 0x3f317217, v48
	v_fma_f32 v130, v48, s94, -v130
	v_fmac_f32_e32 v130, 0x3377d1cf, v48
	v_fmac_f32_e32 v130, 0x3f317217, v48
	v_cmp_lt_f32_e64 s[0:1], |v48|, s95
	s_nop 1
	v_cndmask_b32_e64 v48, v48, v130, s[0:1]
	s_nop 0
	s_nop 0
	v_add_f32_e32 v48, v126, v48
	v_mul_f32_e32 v126, 0xbd800000, v48
	v_mov_b32_e32 v130, v49
	s_nop 1
	v_mov_b32_dpp v130, v126 row_shr:1 row_mask:0xf bank_mask:0xf
	v_fmac_f32_e32 v130, 0xbd800000, v48
	s_nop 1
	v_add_f32_dpp v126, v130, v130 row_shr:2 row_mask:0xf bank_mask:0xf bound_ctrl:1
	v_mov_b32_e32 v130, v49
	s_nop 0
	v_add_f32_dpp v126, v126, v126 row_shr:4 row_mask:0xf bank_mask:0xf bound_ctrl:1
	s_nop 1
	v_add_f32_dpp v126, v126, v126 row_shr:8 row_mask:0xf bank_mask:0xf bound_ctrl:1
	s_nop 1
	v_mov_b32_dpp v130, v126 row_bcast:15 row_mask:0xa bank_mask:0xf
	v_add_f32_e32 v126, v126, v130
	v_mov_b32_e32 v130, v49
	s_nop 1
	v_mov_b32_dpp v130, v126 row_bcast:31 row_mask:0xc bank_mask:0xf
	v_add_f32_e32 v126, v126, v130
	s_nop 0
	v_readlane_b32 s4, v126, 63
	s_nop 1
	v_sub_f32_e32 v130, s4, v126
	v_fmac_f32_e32 v126, 0x3d800000, v48
	v_cndmask_b32_e64 v48, v126, v130, s[8:9]
	s_nop 15
	s_nop 3
	v_mov_b32_e32 v126, v132
	v_max_f32_e64 v127, -v126, 0
	v_mul_f32_e64 v126, |v126|, s93
	v_exp_f32_e32 v126, v126
	v_mul_f32_e32 v48, 0x3fb8aa3b, v48
	v_exp_f32_e32 v48, v48
	v_add_f32_e32 v126, 1.0, v126
	s_nop 0
	s_nop 1
	s_nop 0
	s_nop 0
	v_log_f32_e32 v126, v126
	s_nop 0
	v_mul_f32_e32 v130, 0x3f317217, v126
	v_fma_f32 v130, v126, s94, -v130
	v_fmac_f32_e32 v130, 0x3377d1cf, v126
	v_fmac_f32_e32 v130, 0x3f317217, v126
	v_cmp_lt_f32_e64 s[0:1], |v126|, s95
	s_nop 1
	v_cndmask_b32_e64 v126, v126, v130, s[0:1]
	s_nop 0
	s_nop 0
	v_add_f32_e32 v126, v127, v126
	v_mul_f32_e32 v127, 0xbd800000, v126
	v_mov_b32_e32 v130, v49
	s_nop 1
	v_mov_b32_dpp v130, v127 row_shr:1 row_mask:0xf bank_mask:0xf
	v_fmac_f32_e32 v130, 0xbd800000, v126
	s_nop 1
	v_add_f32_dpp v127, v130, v130 row_shr:2 row_mask:0xf bank_mask:0xf bound_ctrl:1
	v_mov_b32_e32 v130, v49
	s_nop 0
	v_add_f32_dpp v127, v127, v127 row_shr:4 row_mask:0xf bank_mask:0xf bound_ctrl:1
	s_nop 1
	v_add_f32_dpp v127, v127, v127 row_shr:8 row_mask:0xf bank_mask:0xf bound_ctrl:1
	s_nop 1
	v_mov_b32_dpp v130, v127 row_bcast:15 row_mask:0xa bank_mask:0xf
	v_add_f32_e32 v127, v127, v130
	v_mov_b32_e32 v130, v49
	s_nop 1
	v_mov_b32_dpp v130, v127 row_bcast:31 row_mask:0xc bank_mask:0xf
	v_add_f32_e32 v127, v127, v130
	s_nop 0
	v_readlane_b32 s5, v127, 63
	s_nop 1
	v_sub_f32_e32 v130, s5, v127
	v_fmac_f32_e32 v127, 0x3d800000, v126
	v_cndmask_b32_e64 v126, v127, v130, s[8:9]
	s_nop 13
	s_nop 0
	s_nop 7
	v_mov_b32_e32 v127, v133
	v_max_f32_e64 v128, -v127, 0
	v_mul_f32_e64 v127, |v127|, s93
	v_exp_f32_e32 v127, v127
	s_nop 0
	v_add_f32_e32 v127, 1.0, v127
	s_nop 0
	s_nop 1
	s_nop 0
	s_nop 0
	v_log_f32_e32 v127, v127
	s_nop 0
	v_mul_f32_e32 v130, 0x3f317217, v127
	v_fma_f32 v130, v127, s94, -v130
	v_fmac_f32_e32 v130, 0x3377d1cf, v127
	v_fmac_f32_e32 v130, 0x3f317217, v127
	v_cmp_lt_f32_e64 s[0:1], |v127|, s95
	s_nop 1
	v_cndmask_b32_e64 v127, v127, v130, s[0:1]
	s_nop 0
	s_nop 0
	v_add_f32_e32 v127, v128, v127
	v_mul_f32_e32 v128, 0xbd800000, v127
	v_mov_b32_e32 v130, v49
	s_nop 1
	v_mov_b32_dpp v130, v128 row_shr:1 row_mask:0xf bank_mask:0xf
	v_fmac_f32_e32 v130, 0xbd800000, v127
	s_nop 1
	v_add_f32_dpp v128, v130, v130 row_shr:2 row_mask:0xf bank_mask:0xf bound_ctrl:1
	v_mov_b32_e32 v130, v49
	s_nop 0
	v_add_f32_dpp v128, v128, v128 row_shr:4 row_mask:0xf bank_mask:0xf bound_ctrl:1
	s_nop 1
	v_add_f32_dpp v128, v128, v128 row_shr:8 row_mask:0xf bank_mask:0xf bound_ctrl:1
	s_nop 1
	v_mov_b32_dpp v130, v128 row_bcast:15 row_mask:0xa bank_mask:0xf
	v_add_f32_e32 v128, v128, v130
	v_mov_b32_e32 v130, v49
	s_nop 1
	v_mov_b32_dpp v130, v128 row_bcast:31 row_mask:0xc bank_mask:0xf
	v_add_f32_e32 v128, v128, v130
	s_nop 0
	v_readlane_b32 s6, v128, 63
	s_nop 1
	v_sub_f32_e32 v130, s6, v128
	v_fmac_f32_e32 v128, 0x3d800000, v127
	v_cndmask_b32_e64 v127, v128, v130, s[8:9]
	s_nop 0
	s_nop 0
	s_nop 2
	s_nop 0
	s_nop 1
	v_mov_b32_e32 v128, v134
	v_max_f32_e64 v129, -v128, 0
	v_mul_f32_e64 v128, |v128|, s93
	v_exp_f32_e32 v128, v128
	s_nop 0
	v_add_f32_e32 v128, 1.0, v128
	s_nop 0
	s_nop 1
	s_nop 0
	s_nop 0
	v_log_f32_e32 v128, v128
	s_nop 0
	v_mul_f32_e32 v130, 0x3f317217, v128
	v_fma_f32 v130, v128, s94, -v130
	v_fmac_f32_e32 v130, 0x3377d1cf, v128
	v_fmac_f32_e32 v130, 0x3f317217, v128
	v_cmp_lt_f32_e64 s[0:1], |v128|, s95
	s_nop 1
	v_cndmask_b32_e64 v128, v128, v130, s[0:1]
	s_nop 0
	s_nop 0
	v_add_f32_e32 v128, v129, v128
	v_mul_f32_e32 v129, 0xbd800000, v128
	v_mov_b32_e32 v130, v49
	s_nop 1
	v_mov_b32_dpp v130, v129 row_shr:1 row_mask:0xf bank_mask:0xf
	v_fmac_f32_e32 v130, 0xbd800000, v128
	s_nop 1
	v_add_f32_dpp v129, v130, v130 row_shr:2 row_mask:0xf bank_mask:0xf bound_ctrl:1
	v_mov_b32_e32 v130, v49
	s_nop 0
	v_add_f32_dpp v129, v129, v129 row_shr:4 row_mask:0xf bank_mask:0xf bound_ctrl:1
	s_nop 1
	v_add_f32_dpp v129, v129, v129 row_shr:8 row_mask:0xf bank_mask:0xf bound_ctrl:1
	s_nop 1
	v_mov_b32_dpp v130, v129 row_bcast:15 row_mask:0xa bank_mask:0xf
	v_add_f32_e32 v129, v129, v130
	v_mov_b32_e32 v130, v49
	s_nop 1
	v_mov_b32_dpp v130, v129 row_bcast:31 row_mask:0xc bank_mask:0xf
	v_add_f32_e32 v129, v129, v130
	s_nop 0
	v_readlane_b32 s7, v129, 63
	s_nop 1
	v_sub_f32_e32 v130, s7, v129
	v_fmac_f32_e32 v129, 0x3d800000, v128
	v_cndmask_b32_e64 v130, v129, v130, s[8:9]
	s_nop 11
	v_mov_b32_e32 v58, v135
	v_max_f32_e64 v62, -v58, 0
	v_mul_f32_e64 v58, |v58|, s93
	v_exp_f32_e32 v58, v58
	s_nop 0
	v_add_f32_e32 v58, 1.0, v58
	s_nop 0
	s_nop 1
	s_nop 0
	s_nop 0
	v_log_f32_e32 v58, v58
	s_nop 0
	v_mul_f32_e32 v66, 0x3f317217, v58
	v_fma_f32 v66, v58, s94, -v66
	v_fmac_f32_e32 v66, 0x3377d1cf, v58
	v_fmac_f32_e32 v66, 0x3f317217, v58
	v_cmp_lt_f32_e64 s[0:1], |v58|, s95
	s_nop 1
	v_cndmask_b32_e64 v58, v58, v66, s[0:1]
	s_nop 0
	s_nop 0
	v_add_f32_e32 v58, v62, v58
	v_mul_f32_e32 v62, 0xbd800000, v58
	v_mov_b32_e32 v66, v49
	s_nop 1
	v_mov_b32_dpp v66, v62 row_shr:1 row_mask:0xf bank_mask:0xf
	v_fmac_f32_e32 v66, 0xbd800000, v58
	s_nop 1
	v_add_f32_dpp v62, v66, v66 row_shr:2 row_mask:0xf bank_mask:0xf bound_ctrl:1
	v_mov_b32_e32 v66, v49
	s_nop 0
	v_add_f32_dpp v62, v62, v62 row_shr:4 row_mask:0xf bank_mask:0xf bound_ctrl:1
	s_nop 1
	v_add_f32_dpp v62, v62, v62 row_shr:8 row_mask:0xf bank_mask:0xf bound_ctrl:1
	s_nop 1
	v_mov_b32_dpp v66, v62 row_bcast:15 row_mask:0xa bank_mask:0xf
	v_add_f32_e32 v62, v62, v66
	v_mov_b32_e32 v66, v49
	s_nop 1
	v_mov_b32_dpp v66, v62 row_bcast:31 row_mask:0xc bank_mask:0xf
	v_add_f32_e32 v62, v62, v66
	s_nop 0
	v_readlane_b32 s91, v62, 63
	s_nop 1
	v_sub_f32_e32 v66, s91, v62
	v_fmac_f32_e32 v62, 0x3d800000, v58
	s_nop 0
	v_cndmask_b32_e64 v62, v62, v66, s[8:9]
	s_nop 2
	v_lshlrev_b32_e32 v66, 16, v37
	s_nop 1
	v_mov_b32_e32 v58, v136
	v_max_f32_e64 v59, -v58, 0
	v_mul_f32_e64 v58, |v58|, s93
	v_exp_f32_e32 v58, v58
	s_nop 0
	v_add_f32_e32 v58, 1.0, v58
	s_nop 0
	s_nop 1
	s_nop 0
	s_nop 0
	v_log_f32_e32 v58, v58
	s_nop 0
	v_mul_f32_e32 v63, 0x3f317217, v58
	v_fma_f32 v63, v58, s94, -v63
	v_fmac_f32_e32 v63, 0x3377d1cf, v58
	v_fmac_f32_e32 v63, 0x3f317217, v58
	v_cmp_lt_f32_e64 s[0:1], |v58|, s95
	s_nop 1
	v_cndmask_b32_e64 v58, v58, v63, s[0:1]
	s_nop 0
	s_nop 0
	v_add_f32_e32 v58, v59, v58
	v_mul_f32_e32 v59, 0xbd800000, v58
	v_mov_b32_e32 v63, v49
	s_nop 1
	v_mov_b32_dpp v63, v59 row_shr:1 row_mask:0xf bank_mask:0xf
	v_fmac_f32_e32 v63, 0xbd800000, v58
	s_nop 1
	v_add_f32_dpp v59, v63, v63 row_shr:2 row_mask:0xf bank_mask:0xf bound_ctrl:1
	v_mov_b32_e32 v63, v49
	s_nop 0
	v_add_f32_dpp v59, v59, v59 row_shr:4 row_mask:0xf bank_mask:0xf bound_ctrl:1
	s_nop 1
	v_add_f32_dpp v59, v59, v59 row_shr:8 row_mask:0xf bank_mask:0xf bound_ctrl:1
	s_nop 1
	v_mov_b32_dpp v63, v59 row_bcast:15 row_mask:0xa bank_mask:0xf
	v_add_f32_e32 v59, v59, v63
	v_mov_b32_e32 v63, v49
	s_nop 1
	v_mov_b32_dpp v63, v59 row_bcast:31 row_mask:0xc bank_mask:0xf
	v_add_f32_e32 v59, v59, v63
	s_nop 0
	v_readlane_b32 s20, v59, 63
	s_nop 1
	v_sub_f32_e32 v63, s20, v59
	v_fmac_f32_e32 v59, 0x3d800000, v58
	v_cndmask_b32_e64 v63, v59, v63, s[8:9]
	s_nop 11
	v_mov_b32_e32 v58, v137
	v_max_f32_e64 v59, -v58, 0
	v_mul_f32_e64 v58, |v58|, s93
	v_exp_f32_e32 v58, v58
	s_nop 0
	v_add_f32_e32 v58, 1.0, v58
	s_nop 0
	s_nop 1
	s_nop 0
	s_nop 0
	v_log_f32_e32 v58, v58
	s_nop 0
	v_mul_f32_e32 v60, 0x3f317217, v58
	v_fma_f32 v60, v58, s94, -v60
	v_fmac_f32_e32 v60, 0x3377d1cf, v58
	v_fmac_f32_e32 v60, 0x3f317217, v58
	v_cmp_lt_f32_e64 s[0:1], |v58|, s95
	s_nop 1
	v_cndmask_b32_e64 v58, v58, v60, s[0:1]
	s_nop 0
	s_nop 0
	v_add_f32_e32 v58, v59, v58
	v_mul_f32_e32 v59, 0xbd800000, v58
	v_mov_b32_e32 v60, v49
	s_nop 1
	v_mov_b32_dpp v60, v59 row_shr:1 row_mask:0xf bank_mask:0xf
	v_fmac_f32_e32 v60, 0xbd800000, v58
	s_nop 1
	v_add_f32_dpp v59, v60, v60 row_shr:2 row_mask:0xf bank_mask:0xf bound_ctrl:1
	v_mov_b32_e32 v60, v49
	s_nop 0
	v_add_f32_dpp v59, v59, v59 row_shr:4 row_mask:0xf bank_mask:0xf bound_ctrl:1
	s_nop 1
	v_add_f32_dpp v59, v59, v59 row_shr:8 row_mask:0xf bank_mask:0xf bound_ctrl:1
	s_nop 1
	v_mov_b32_dpp v60, v59 row_bcast:15 row_mask:0xa bank_mask:0xf
	v_add_f32_e32 v59, v59, v60
	v_mov_b32_e32 v60, v49
	s_nop 1
	v_mov_b32_dpp v60, v59 row_bcast:31 row_mask:0xc bank_mask:0xf
	v_add_f32_e32 v59, v59, v60
	s_nop 0
	v_readlane_b32 s21, v59, 63
	s_nop 1
	v_sub_f32_e32 v60, s21, v59
	v_fmac_f32_e32 v59, 0x3d800000, v58
	v_cndmask_b32_e64 v60, v59, v60, s[8:9]
	s_nop 0
	s_nop 0
	s_nop 2
	s_nop 0
	s_nop 1
	v_mov_b32_e32 v58, v138
	v_max_f32_e64 v59, -v58, 0
	v_mul_f32_e64 v58, |v58|, s93
	v_exp_f32_e32 v58, v58
	s_nop 0
	v_add_f32_e32 v58, 1.0, v58
	s_nop 0
	s_nop 1
	s_nop 0
	s_nop 0
	v_log_f32_e32 v58, v58
	s_nop 0
	v_mul_f32_e32 v61, 0x3f317217, v58
	v_fma_f32 v61, v58, s94, -v61
	v_fmac_f32_e32 v61, 0x3377d1cf, v58
	v_fmac_f32_e32 v61, 0x3f317217, v58
	v_cmp_lt_f32_e64 s[0:1], |v58|, s95
	s_nop 1
	v_cndmask_b32_e64 v58, v58, v61, s[0:1]
	s_nop 0
	s_nop 0
	v_add_f32_e32 v58, v59, v58
	v_mul_f32_e32 v59, 0xbd800000, v58
	v_mov_b32_e32 v61, v49
	v_readlane_b32 s0, v254, 0
	s_add_u32 s0, s90, s0
	v_mov_b32_dpp v61, v59 row_shr:1 row_mask:0xf bank_mask:0xf
	v_fmac_f32_e32 v61, 0xbd800000, v58
	v_readlane_b32 s1, v254, 1
	s_addc_u32 s1, s15, s1
	v_add_f32_dpp v59, v61, v61 row_shr:2 row_mask:0xf bank_mask:0xf bound_ctrl:1
	v_mov_b32_e32 v61, v49
	s_lshl_b64 s[0:1], s[0:1], 10
	v_add_f32_dpp v59, v59, v59 row_shr:4 row_mask:0xf bank_mask:0xf bound_ctrl:1
	s_nop 1
	v_add_f32_dpp v59, v59, v59 row_shr:8 row_mask:0xf bank_mask:0xf bound_ctrl:1
	s_nop 1
	v_mov_b32_dpp v61, v59 row_bcast:15 row_mask:0xa bank_mask:0xf
	v_add_f32_e32 v59, v59, v61
	v_mov_b32_e32 v61, v49
	s_nop 1
	v_mov_b32_dpp v61, v59 row_bcast:31 row_mask:0xc bank_mask:0xf
	v_add_f32_e32 v59, v59, v61
	s_nop 0
	v_readlane_b32 s18, v59, 63
	s_nop 1
	v_sub_f32_e32 v61, s18, v59
	v_fmac_f32_e32 v59, 0x3d800000, v58
	v_cndmask_b32_e64 v58, v59, v61, s[8:9]
	v_mul_f32_e32 v59, 0x3fb8aa3b, v126
	v_exp_f32_e32 v72, v59
	v_mul_f32_e32 v59, 0x3fb8aa3b, v127
	v_mul_f32_e32 v58, 0x3fb8aa3b, v58
	v_exp_f32_e32 v73, v59
	v_exp_f32_e32 v78, v58
	v_cvt_pk_bf16_f32 v58, v48, v72
	v_mul_f32_e32 v48, v48, v64
	v_mul_f32_e32 v59, 0x3fb8aa3b, v130
	v_cvt_pk_bf16_f32 v48, v48, s0
	v_exp_f32_e32 v74, v59
	ds_write_b16 v208, v48 offset:56448
	v_mul_f32_e32 v48, v72, v65
	v_mul_f32_e32 v59, 0x3fb8aa3b, v62
	v_cvt_pk_bf16_f32 v48, v48, s0
	v_exp_f32_e32 v75, v59
	ds_write_b16 v208, v48 offset:56592
	v_mul_f32_e32 v48, v73, v66
	v_mul_f32_e32 v59, 0x3fb8aa3b, v63
	v_cvt_pk_bf16_f32 v48, v48, s0
	v_exp_f32_e32 v76, v59
	ds_write_b16 v208, v48 offset:56736
	v_mul_f32_e32 v48, v74, v67
	v_mul_f32_e32 v59, 0x3fb8aa3b, v60
	v_cvt_pk_bf16_f32 v48, v48, s0
	v_exp_f32_e32 v77, v59
	ds_write_b16 v208, v48 offset:56880
	v_mul_f32_e32 v48, v75, v68
	v_cvt_pk_bf16_f32 v48, v48, s0
	ds_write_b16 v208, v48 offset:57024
	v_mul_f32_e32 v48, v76, v69
	v_cvt_pk_bf16_f32 v48, v48, s0
	ds_write_b16 v208, v48 offset:57168
	v_mul_f32_e32 v48, v77, v70
	v_cvt_pk_bf16_f32 v48, v48, s0
	ds_write_b16 v208, v48 offset:57312
	v_mul_f32_e32 v48, v78, v71
	v_cvt_pk_bf16_f32 v59, v73, v74
	v_cvt_pk_bf16_f32 v60, v75, v76
	v_cvt_pk_bf16_f32 v61, v77, v78
	v_lshl_add_u64 v[62:63], v[202:203], 0, s[0:1]
	v_cvt_pk_bf16_f32 v48, v48, s0
	global_store_dwordx4 v[62:63], v[58:61], off
	ds_write_b16 v208, v48 offset:57456
	s_and_saveexec_b64 s[0:1], s[10:11]
	s_cbranch_execz .LBB0_661
	v_mul_f32_e32 v48, s4, v240
	v_exp_f32_e32 v58, v48
	v_mul_f32_e32 v48, s5, v240
	v_exp_f32_e32 v59, v48
	v_mul_f32_e32 v48, s6, v240
	v_exp_f32_e32 v60, v48
	v_mul_f32_e32 v48, s7, v240
	v_exp_f32_e32 v61, v48
	v_mul_f32_e32 v48, s91, v240
	v_exp_f32_e32 v62, v48
	v_mul_f32_e32 v48, s20, v240
	v_exp_f32_e32 v63, v48
	v_mul_f32_e32 v48, s21, v240
	v_exp_f32_e32 v64, v48
	v_mul_f32_e32 v48, s18, v240
	v_exp_f32_e32 v65, v48
	s_add_u32 s4, s16, s88
	s_addc_u32 s5, s17, s89
	global_store_dwordx4 v49, v[58:61], s[4:5] offset:32
	global_store_dwordx4 v49, v[62:65], s[4:5] offset:48
.LBB0_661:
	s_or_b64 exec, exec, s[0:1]
	v_readlane_b32 s0, v254, 63
	v_readlane_b32 s1, v255, 0
	s_nop 15
	s_nop 2
	s_waitcnt lgkmcnt(8)
	s_nop 3
	s_waitcnt lgkmcnt(8)
	v_readlane_b32 s0, v255, 1
	v_readlane_b32 s1, v255, 2
	s_nop 4
	s_nop 1
	v_readlane_b32 s0, v255, 3
	v_readlane_b32 s1, v255, 4
	s_nop 4
	s_nop 1
	s_waitcnt lgkmcnt(8)
	v_readlane_b32 s0, v255, 5
	v_readlane_b32 s1, v255, 6
	s_nop 4
	s_nop 1
	v_readlane_b32 s0, v255, 7
	v_readlane_b32 s1, v255, 8
	s_nop 4
	s_nop 1
	s_waitcnt lgkmcnt(8)
	v_readlane_b32 s0, v255, 9
	v_readlane_b32 s1, v255, 10
	s_nop 4
	s_nop 1
	v_readlane_b32 s0, v255, 11
	v_readlane_b32 s1, v255, 12
	s_nop 4
	s_nop 1
	s_waitcnt lgkmcnt(8)
	v_readlane_b32 s0, v255, 13
	v_readlane_b32 s1, v255, 14
	s_nop 4
	s_nop 1
	v_readlane_b32 s0, v255, 15
	v_readlane_b32 s1, v255, 16
	s_waitcnt lgkmcnt(14)
	s_nop 0
	s_waitcnt lgkmcnt(14)
	s_nop 0
	s_waitcnt lgkmcnt(14)
	s_nop 0
	s_waitcnt lgkmcnt(14)
	s_nop 0
	s_waitcnt lgkmcnt(14)
	s_nop 0
	s_waitcnt lgkmcnt(14)
	s_nop 0
	s_waitcnt lgkmcnt(14)
	s_nop 0
	s_waitcnt lgkmcnt(14)
	s_nop 2
	s_waitcnt lgkmcnt(12)
	s_nop 2
	s_waitcnt lgkmcnt(10)
	s_nop 2
	s_waitcnt lgkmcnt(8)
	s_nop 2
	s_waitcnt lgkmcnt(6)
	s_nop 2
	s_waitcnt lgkmcnt(4)
	s_nop 2
	s_waitcnt lgkmcnt(2)
	s_nop 2
	s_waitcnt lgkmcnt(0)
	s_nop 13
	v_readlane_b32 s0, v255, 17
	v_readlane_b32 s1, v255, 18
	s_nop 4
	s_nop 15
	s_nop 15
	s_nop 14
	v_lshlrev_b32_e32 v64, 16, v40
	v_and_b32_e32 v65, 0xffff0000, v40
	v_and_b32_e32 v67, 0xffff0000, v41
	v_lshlrev_b32_e32 v68, 16, v42
	v_and_b32_e32 v69, 0xffff0000, v42
	v_lshlrev_b32_e32 v70, 16, v43
	v_and_b32_e32 v71, 0xffff0000, v43
	s_waitcnt lgkmcnt(2)
	s_nop 0
	s_waitcnt lgkmcnt(0)
	s_nop 4
	v_mov_b32_e32 v48, v139
	v_max_f32_e64 v126, -v48, 0
	v_mul_f32_e64 v48, |v48|, s93
	v_exp_f32_e32 v48, v48
	s_nop 0
	v_add_f32_e32 v48, 1.0, v48
	s_nop 0
	s_nop 1
	s_nop 0
	s_nop 0
	v_log_f32_e32 v48, v48
	s_nop 0
	v_mul_f32_e32 v130, 0x3f317217, v48
	v_fma_f32 v130, v48, s94, -v130
	v_fmac_f32_e32 v130, 0x3377d1cf, v48
	v_fmac_f32_e32 v130, 0x3f317217, v48
	v_cmp_lt_f32_e64 s[0:1], |v48|, s95
	s_nop 1
	v_cndmask_b32_e64 v48, v48, v130, s[0:1]
	s_nop 0
	s_nop 0
	v_add_f32_e32 v48, v126, v48
	v_mul_f32_e32 v126, 0xbd800000, v48
	v_mov_b32_e32 v130, v49
	s_nop 1
	v_mov_b32_dpp v130, v126 row_shr:1 row_mask:0xf bank_mask:0xf
	v_fmac_f32_e32 v130, 0xbd800000, v48
	s_nop 1
	v_add_f32_dpp v126, v130, v130 row_shr:2 row_mask:0xf bank_mask:0xf bound_ctrl:1
	v_mov_b32_e32 v130, v49
	s_nop 0
	v_add_f32_dpp v126, v126, v126 row_shr:4 row_mask:0xf bank_mask:0xf bound_ctrl:1
	s_nop 1
	v_add_f32_dpp v126, v126, v126 row_shr:8 row_mask:0xf bank_mask:0xf bound_ctrl:1
	s_nop 1
	v_mov_b32_dpp v130, v126 row_bcast:15 row_mask:0xa bank_mask:0xf
	v_add_f32_e32 v126, v126, v130
	v_mov_b32_e32 v130, v49
	s_nop 1
	v_mov_b32_dpp v130, v126 row_bcast:31 row_mask:0xc bank_mask:0xf
	v_add_f32_e32 v126, v126, v130
	s_nop 0
	v_readlane_b32 s4, v126, 63
	s_nop 1
	v_sub_f32_e32 v130, s4, v126
	v_fmac_f32_e32 v126, 0x3d800000, v48
	v_cndmask_b32_e64 v48, v126, v130, s[8:9]
	s_nop 15
	s_nop 3
	v_mov_b32_e32 v126, v140
	v_max_f32_e64 v127, -v126, 0
	v_mul_f32_e64 v126, |v126|, s93
	v_exp_f32_e32 v126, v126
	v_mul_f32_e32 v48, 0x3fb8aa3b, v48
	v_exp_f32_e32 v48, v48
	v_add_f32_e32 v126, 1.0, v126
	s_nop 0
	s_nop 1
	s_nop 0
	s_nop 0
	v_log_f32_e32 v126, v126
	s_nop 0
	v_mul_f32_e32 v130, 0x3f317217, v126
	v_fma_f32 v130, v126, s94, -v130
	v_fmac_f32_e32 v130, 0x3377d1cf, v126
	v_fmac_f32_e32 v130, 0x3f317217, v126
	v_cmp_lt_f32_e64 s[0:1], |v126|, s95
	s_nop 1
	v_cndmask_b32_e64 v126, v126, v130, s[0:1]
	s_nop 0
	s_nop 0
	v_add_f32_e32 v126, v127, v126
	v_mul_f32_e32 v127, 0xbd800000, v126
	v_mov_b32_e32 v130, v49
	s_nop 1
	v_mov_b32_dpp v130, v127 row_shr:1 row_mask:0xf bank_mask:0xf
	v_fmac_f32_e32 v130, 0xbd800000, v126
	s_nop 1
	v_add_f32_dpp v127, v130, v130 row_shr:2 row_mask:0xf bank_mask:0xf bound_ctrl:1
	v_mov_b32_e32 v130, v49
	s_nop 0
	v_add_f32_dpp v127, v127, v127 row_shr:4 row_mask:0xf bank_mask:0xf bound_ctrl:1
	s_nop 1
	v_add_f32_dpp v127, v127, v127 row_shr:8 row_mask:0xf bank_mask:0xf bound_ctrl:1
	s_nop 1
	v_mov_b32_dpp v130, v127 row_bcast:15 row_mask:0xa bank_mask:0xf
	v_add_f32_e32 v127, v127, v130
	v_mov_b32_e32 v130, v49
	s_nop 1
	v_mov_b32_dpp v130, v127 row_bcast:31 row_mask:0xc bank_mask:0xf
	v_add_f32_e32 v127, v127, v130
	s_nop 0
	v_readlane_b32 s5, v127, 63
	s_nop 1
	v_sub_f32_e32 v130, s5, v127
	v_fmac_f32_e32 v127, 0x3d800000, v126
	v_cndmask_b32_e64 v126, v127, v130, s[8:9]
	s_nop 13
	s_nop 0
	s_nop 7
	v_mov_b32_e32 v127, v141
	v_max_f32_e64 v128, -v127, 0
	v_mul_f32_e64 v127, |v127|, s93
	v_exp_f32_e32 v127, v127
	s_nop 0
	v_add_f32_e32 v127, 1.0, v127
	s_nop 0
	s_nop 1
	s_nop 0
	s_nop 0
	v_log_f32_e32 v127, v127
	s_nop 0
	v_mul_f32_e32 v130, 0x3f317217, v127
	v_fma_f32 v130, v127, s94, -v130
	v_fmac_f32_e32 v130, 0x3377d1cf, v127
	v_fmac_f32_e32 v130, 0x3f317217, v127
	v_cmp_lt_f32_e64 s[0:1], |v127|, s95
	s_nop 1
	v_cndmask_b32_e64 v127, v127, v130, s[0:1]
	s_nop 0
	s_nop 0
	v_add_f32_e32 v127, v128, v127
	v_mul_f32_e32 v128, 0xbd800000, v127
	v_mov_b32_e32 v130, v49
	s_nop 1
	v_mov_b32_dpp v130, v128 row_shr:1 row_mask:0xf bank_mask:0xf
	v_fmac_f32_e32 v130, 0xbd800000, v127
	s_nop 1
	v_add_f32_dpp v128, v130, v130 row_shr:2 row_mask:0xf bank_mask:0xf bound_ctrl:1
	v_mov_b32_e32 v130, v49
	s_nop 0
	v_add_f32_dpp v128, v128, v128 row_shr:4 row_mask:0xf bank_mask:0xf bound_ctrl:1
	s_nop 1
	v_add_f32_dpp v128, v128, v128 row_shr:8 row_mask:0xf bank_mask:0xf bound_ctrl:1
	s_nop 1
	v_mov_b32_dpp v130, v128 row_bcast:15 row_mask:0xa bank_mask:0xf
	v_add_f32_e32 v128, v128, v130
	v_mov_b32_e32 v130, v49
	s_nop 1
	v_mov_b32_dpp v130, v128 row_bcast:31 row_mask:0xc bank_mask:0xf
	v_add_f32_e32 v128, v128, v130
	s_nop 0
	v_readlane_b32 s6, v128, 63
	s_nop 1
	v_sub_f32_e32 v130, s6, v128
	v_fmac_f32_e32 v128, 0x3d800000, v127
	v_cndmask_b32_e64 v127, v128, v130, s[8:9]
	s_nop 0
	s_nop 0
	s_nop 2
	s_nop 0
	s_nop 1
	v_mov_b32_e32 v128, v142
	v_max_f32_e64 v129, -v128, 0
	v_mul_f32_e64 v128, |v128|, s93
	v_exp_f32_e32 v128, v128
	s_nop 0
	v_add_f32_e32 v128, 1.0, v128
	s_nop 0
	s_nop 1
	s_nop 0
	s_nop 0
	v_log_f32_e32 v128, v128
	s_nop 0
	v_mul_f32_e32 v130, 0x3f317217, v128
	v_fma_f32 v130, v128, s94, -v130
	v_fmac_f32_e32 v130, 0x3377d1cf, v128
	v_fmac_f32_e32 v130, 0x3f317217, v128
	v_cmp_lt_f32_e64 s[0:1], |v128|, s95
	s_nop 1
	v_cndmask_b32_e64 v128, v128, v130, s[0:1]
	s_nop 0
	s_nop 0
	v_add_f32_e32 v128, v129, v128
	v_mul_f32_e32 v129, 0xbd800000, v128
	v_mov_b32_e32 v130, v49
	s_nop 1
	v_mov_b32_dpp v130, v129 row_shr:1 row_mask:0xf bank_mask:0xf
	v_fmac_f32_e32 v130, 0xbd800000, v128
	s_nop 1
	v_add_f32_dpp v129, v130, v130 row_shr:2 row_mask:0xf bank_mask:0xf bound_ctrl:1
	v_mov_b32_e32 v130, v49
	s_nop 0
	v_add_f32_dpp v129, v129, v129 row_shr:4 row_mask:0xf bank_mask:0xf bound_ctrl:1
	s_nop 1
	v_add_f32_dpp v129, v129, v129 row_shr:8 row_mask:0xf bank_mask:0xf bound_ctrl:1
	s_nop 1
	v_mov_b32_dpp v130, v129 row_bcast:15 row_mask:0xa bank_mask:0xf
	v_add_f32_e32 v129, v129, v130
	v_mov_b32_e32 v130, v49
	s_nop 1
	v_mov_b32_dpp v130, v129 row_bcast:31 row_mask:0xc bank_mask:0xf
	v_add_f32_e32 v129, v129, v130
	s_nop 0
	v_readlane_b32 s7, v129, 63
	s_nop 1
	v_sub_f32_e32 v130, s7, v129
	v_fmac_f32_e32 v129, 0x3d800000, v128
	v_cndmask_b32_e64 v130, v129, v130, s[8:9]
	s_nop 11
	v_mov_b32_e32 v58, v143
	v_max_f32_e64 v62, -v58, 0
	v_mul_f32_e64 v58, |v58|, s93
	v_exp_f32_e32 v58, v58
	s_nop 0
	v_add_f32_e32 v58, 1.0, v58
	s_nop 0
	s_nop 1
	s_nop 0
	s_nop 0
	v_log_f32_e32 v58, v58
	s_nop 0
	v_mul_f32_e32 v66, 0x3f317217, v58
	v_fma_f32 v66, v58, s94, -v66
	v_fmac_f32_e32 v66, 0x3377d1cf, v58
	v_fmac_f32_e32 v66, 0x3f317217, v58
	v_cmp_lt_f32_e64 s[0:1], |v58|, s95
	s_nop 1
	v_cndmask_b32_e64 v58, v58, v66, s[0:1]
	s_nop 0
	s_nop 0
	v_add_f32_e32 v58, v62, v58
	v_mul_f32_e32 v62, 0xbd800000, v58
	v_mov_b32_e32 v66, v49
	s_nop 1
	v_mov_b32_dpp v66, v62 row_shr:1 row_mask:0xf bank_mask:0xf
	v_fmac_f32_e32 v66, 0xbd800000, v58
	s_nop 1
	v_add_f32_dpp v62, v66, v66 row_shr:2 row_mask:0xf bank_mask:0xf bound_ctrl:1
	v_mov_b32_e32 v66, v49
	s_nop 0
	v_add_f32_dpp v62, v62, v62 row_shr:4 row_mask:0xf bank_mask:0xf bound_ctrl:1
	s_nop 1
	v_add_f32_dpp v62, v62, v62 row_shr:8 row_mask:0xf bank_mask:0xf bound_ctrl:1
	s_nop 1
	v_mov_b32_dpp v66, v62 row_bcast:15 row_mask:0xa bank_mask:0xf
	v_add_f32_e32 v62, v62, v66
	v_mov_b32_e32 v66, v49
	s_nop 1
	v_mov_b32_dpp v66, v62 row_bcast:31 row_mask:0xc bank_mask:0xf
	v_add_f32_e32 v62, v62, v66
	s_nop 0
	v_readlane_b32 s91, v62, 63
	s_nop 1
	v_sub_f32_e32 v66, s91, v62
	v_fmac_f32_e32 v62, 0x3d800000, v58
	s_nop 0
	v_cndmask_b32_e64 v62, v62, v66, s[8:9]
	s_nop 2
	v_lshlrev_b32_e32 v66, 16, v41
	s_nop 1
	v_mov_b32_e32 v58, v144
	v_max_f32_e64 v59, -v58, 0
	v_mul_f32_e64 v58, |v58|, s93
	v_exp_f32_e32 v58, v58
	s_nop 0
	v_add_f32_e32 v58, 1.0, v58
	s_nop 0
	s_nop 1
	s_nop 0
	s_nop 0
	v_log_f32_e32 v58, v58
	s_nop 0
	v_mul_f32_e32 v63, 0x3f317217, v58
	v_fma_f32 v63, v58, s94, -v63
	v_fmac_f32_e32 v63, 0x3377d1cf, v58
	v_fmac_f32_e32 v63, 0x3f317217, v58
	v_cmp_lt_f32_e64 s[0:1], |v58|, s95
	s_nop 1
	v_cndmask_b32_e64 v58, v58, v63, s[0:1]
	s_nop 0
	s_nop 0
	v_add_f32_e32 v58, v59, v58
	v_mul_f32_e32 v59, 0xbd800000, v58
	v_mov_b32_e32 v63, v49
	s_nop 1
	v_mov_b32_dpp v63, v59 row_shr:1 row_mask:0xf bank_mask:0xf
	v_fmac_f32_e32 v63, 0xbd800000, v58
	s_nop 1
	v_add_f32_dpp v59, v63, v63 row_shr:2 row_mask:0xf bank_mask:0xf bound_ctrl:1
	v_mov_b32_e32 v63, v49
	s_nop 0
	v_add_f32_dpp v59, v59, v59 row_shr:4 row_mask:0xf bank_mask:0xf bound_ctrl:1
	s_nop 1
	v_add_f32_dpp v59, v59, v59 row_shr:8 row_mask:0xf bank_mask:0xf bound_ctrl:1
	s_nop 1
	v_mov_b32_dpp v63, v59 row_bcast:15 row_mask:0xa bank_mask:0xf
	v_add_f32_e32 v59, v59, v63
	v_mov_b32_e32 v63, v49
	s_nop 1
	v_mov_b32_dpp v63, v59 row_bcast:31 row_mask:0xc bank_mask:0xf
	v_add_f32_e32 v59, v59, v63
	s_nop 0
	v_readlane_b32 s20, v59, 63
	s_nop 1
	v_sub_f32_e32 v63, s20, v59
	v_fmac_f32_e32 v59, 0x3d800000, v58
	v_cndmask_b32_e64 v63, v59, v63, s[8:9]
	s_nop 11
	v_mov_b32_e32 v58, v145
	v_max_f32_e64 v59, -v58, 0
	v_mul_f32_e64 v58, |v58|, s93
	v_exp_f32_e32 v58, v58
	s_nop 0
	v_add_f32_e32 v58, 1.0, v58
	s_nop 0
	s_nop 1
	s_nop 0
	s_nop 0
	v_log_f32_e32 v58, v58
	s_nop 0
	v_mul_f32_e32 v60, 0x3f317217, v58
	v_fma_f32 v60, v58, s94, -v60
	v_fmac_f32_e32 v60, 0x3377d1cf, v58
	v_fmac_f32_e32 v60, 0x3f317217, v58
	v_cmp_lt_f32_e64 s[0:1], |v58|, s95
	s_nop 1
	v_cndmask_b32_e64 v58, v58, v60, s[0:1]
	s_nop 0
	s_nop 0
	v_add_f32_e32 v58, v59, v58
	v_mul_f32_e32 v59, 0xbd800000, v58
	v_mov_b32_e32 v60, v49
	s_nop 1
	v_mov_b32_dpp v60, v59 row_shr:1 row_mask:0xf bank_mask:0xf
	v_fmac_f32_e32 v60, 0xbd800000, v58
	s_nop 1
	v_add_f32_dpp v59, v60, v60 row_shr:2 row_mask:0xf bank_mask:0xf bound_ctrl:1
	v_mov_b32_e32 v60, v49
	s_nop 0
	v_add_f32_dpp v59, v59, v59 row_shr:4 row_mask:0xf bank_mask:0xf bound_ctrl:1
	s_nop 1
	v_add_f32_dpp v59, v59, v59 row_shr:8 row_mask:0xf bank_mask:0xf bound_ctrl:1
	s_nop 1
	v_mov_b32_dpp v60, v59 row_bcast:15 row_mask:0xa bank_mask:0xf
	v_add_f32_e32 v59, v59, v60
	v_mov_b32_e32 v60, v49
	s_nop 1
	v_mov_b32_dpp v60, v59 row_bcast:31 row_mask:0xc bank_mask:0xf
	v_add_f32_e32 v59, v59, v60
	s_nop 0
	v_readlane_b32 s21, v59, 63
	s_nop 1
	v_sub_f32_e32 v60, s21, v59
	v_fmac_f32_e32 v59, 0x3d800000, v58
	v_cndmask_b32_e64 v60, v59, v60, s[8:9]
	s_nop 0
	s_nop 0
	s_nop 2
	s_nop 0
	s_nop 1
	v_mov_b32_e32 v58, v146
	v_max_f32_e64 v59, -v58, 0
	v_mul_f32_e64 v58, |v58|, s93
	v_exp_f32_e32 v58, v58
	s_nop 0
	v_add_f32_e32 v58, 1.0, v58
	s_nop 0
	s_nop 1
	s_nop 0
	s_nop 0
	v_log_f32_e32 v58, v58
	s_nop 0
	v_mul_f32_e32 v61, 0x3f317217, v58
	v_fma_f32 v61, v58, s94, -v61
	v_fmac_f32_e32 v61, 0x3377d1cf, v58
	v_fmac_f32_e32 v61, 0x3f317217, v58
	v_cmp_lt_f32_e64 s[0:1], |v58|, s95
	s_nop 1
	v_cndmask_b32_e64 v58, v58, v61, s[0:1]
	s_nop 0
	s_nop 0
	v_add_f32_e32 v58, v59, v58
	v_mul_f32_e32 v59, 0xbd800000, v58
	v_mov_b32_e32 v61, v49
	v_readlane_b32 s0, v254, 2
	s_add_u32 s0, s90, s0
	v_mov_b32_dpp v61, v59 row_shr:1 row_mask:0xf bank_mask:0xf
	v_fmac_f32_e32 v61, 0xbd800000, v58
	v_readlane_b32 s1, v254, 4
	s_addc_u32 s1, s15, s1
	v_add_f32_dpp v59, v61, v61 row_shr:2 row_mask:0xf bank_mask:0xf bound_ctrl:1
	v_mov_b32_e32 v61, v49
	s_lshl_b64 s[0:1], s[0:1], 10
	v_add_f32_dpp v59, v59, v59 row_shr:4 row_mask:0xf bank_mask:0xf bound_ctrl:1
	s_nop 1
	v_add_f32_dpp v59, v59, v59 row_shr:8 row_mask:0xf bank_mask:0xf bound_ctrl:1
	s_nop 1
	v_mov_b32_dpp v61, v59 row_bcast:15 row_mask:0xa bank_mask:0xf
	v_add_f32_e32 v59, v59, v61
	v_mov_b32_e32 v61, v49
	s_nop 1
	v_mov_b32_dpp v61, v59 row_bcast:31 row_mask:0xc bank_mask:0xf
	v_add_f32_e32 v59, v59, v61
	s_nop 0
	v_readlane_b32 s18, v59, 63
	s_nop 1
	v_sub_f32_e32 v61, s18, v59
	v_fmac_f32_e32 v59, 0x3d800000, v58
	v_cndmask_b32_e64 v58, v59, v61, s[8:9]
	v_mul_f32_e32 v59, 0x3fb8aa3b, v126
	v_exp_f32_e32 v72, v59
	v_mul_f32_e32 v59, 0x3fb8aa3b, v127
	v_mul_f32_e32 v58, 0x3fb8aa3b, v58
	v_exp_f32_e32 v73, v59
	v_exp_f32_e32 v78, v58
	v_cvt_pk_bf16_f32 v58, v48, v72
	v_mul_f32_e32 v48, v48, v64
	v_mul_f32_e32 v59, 0x3fb8aa3b, v130
	v_cvt_pk_bf16_f32 v48, v48, s0
	v_exp_f32_e32 v74, v59
	ds_write_b16 v208, v48 offset:57600
	v_mul_f32_e32 v48, v72, v65
	v_mul_f32_e32 v59, 0x3fb8aa3b, v62
	v_cvt_pk_bf16_f32 v48, v48, s0
	v_exp_f32_e32 v75, v59
	ds_write_b16 v208, v48 offset:57744
	v_mul_f32_e32 v48, v73, v66
	v_mul_f32_e32 v59, 0x3fb8aa3b, v63
	v_cvt_pk_bf16_f32 v48, v48, s0
	v_exp_f32_e32 v76, v59
	ds_write_b16 v208, v48 offset:57888
	v_mul_f32_e32 v48, v74, v67
	v_mul_f32_e32 v59, 0x3fb8aa3b, v60
	v_cvt_pk_bf16_f32 v48, v48, s0
	v_exp_f32_e32 v77, v59
	ds_write_b16 v208, v48 offset:58032
	v_mul_f32_e32 v48, v75, v68
	v_cvt_pk_bf16_f32 v48, v48, s0
	ds_write_b16 v208, v48 offset:58176
	v_mul_f32_e32 v48, v76, v69
	v_cvt_pk_bf16_f32 v48, v48, s0
	ds_write_b16 v208, v48 offset:58320
	v_mul_f32_e32 v48, v77, v70
	v_cvt_pk_bf16_f32 v48, v48, s0
	ds_write_b16 v208, v48 offset:58464
	v_mul_f32_e32 v48, v78, v71
	v_cvt_pk_bf16_f32 v59, v73, v74
	v_cvt_pk_bf16_f32 v60, v75, v76
	v_cvt_pk_bf16_f32 v61, v77, v78
	v_lshl_add_u64 v[62:63], v[202:203], 0, s[0:1]
	v_cvt_pk_bf16_f32 v48, v48, s0
	global_store_dwordx4 v[62:63], v[58:61], off
	ds_write_b16 v208, v48 offset:58608
	s_and_saveexec_b64 s[0:1], s[10:11]
	s_cbranch_execz .LBB0_663
	v_mul_f32_e32 v48, s4, v240
	v_exp_f32_e32 v58, v48
	v_mul_f32_e32 v48, s5, v240
	v_exp_f32_e32 v59, v48
	v_mul_f32_e32 v48, s6, v240
	v_exp_f32_e32 v60, v48
	v_mul_f32_e32 v48, s7, v240
	v_exp_f32_e32 v61, v48
	v_mul_f32_e32 v48, s91, v240
	v_exp_f32_e32 v62, v48
	v_mul_f32_e32 v48, s20, v240
	v_exp_f32_e32 v63, v48
	v_mul_f32_e32 v48, s21, v240
	v_exp_f32_e32 v64, v48
	v_mul_f32_e32 v48, s18, v240
	v_exp_f32_e32 v65, v48
	s_add_u32 s4, s16, s88
	s_addc_u32 s5, s17, s89
	global_store_dwordx4 v49, v[58:61], s[4:5] offset:64
	global_store_dwordx4 v49, v[62:65], s[4:5] offset:80
.LBB0_663:
	s_or_b64 exec, exec, s[0:1]
	v_readlane_b32 s0, v255, 19
	v_readlane_b32 s1, v255, 20
	s_nop 15
	s_nop 2
	s_waitcnt lgkmcnt(8)
	s_nop 3
	s_waitcnt lgkmcnt(8)
	v_readlane_b32 s0, v255, 21
	v_readlane_b32 s1, v255, 22
	s_nop 4
	s_nop 1
	v_readlane_b32 s0, v255, 23
	v_readlane_b32 s1, v255, 24
	s_nop 4
	s_nop 1
	s_waitcnt lgkmcnt(8)
	v_readlane_b32 s0, v255, 25
	v_readlane_b32 s1, v255, 26
	s_nop 4
	s_nop 1
	v_readlane_b32 s0, v255, 27
	v_readlane_b32 s1, v255, 28
	s_nop 4
	s_nop 1
	s_waitcnt lgkmcnt(8)
	v_readlane_b32 s0, v255, 29
	v_readlane_b32 s1, v255, 30
	s_nop 4
	s_nop 1
	v_readlane_b32 s0, v255, 31
	v_readlane_b32 s1, v255, 32
	s_nop 4
	s_nop 1
	s_waitcnt lgkmcnt(8)
	v_readlane_b32 s0, v255, 33
	v_readlane_b32 s1, v255, 34
	s_nop 4
	s_nop 1
	v_readlane_b32 s0, v255, 35
	v_readlane_b32 s1, v255, 36
	s_waitcnt lgkmcnt(14)
	s_nop 0
	s_waitcnt lgkmcnt(14)
	s_nop 0
	s_waitcnt lgkmcnt(14)
	s_nop 0
	s_waitcnt lgkmcnt(14)
	s_nop 0
	s_waitcnt lgkmcnt(14)
	s_nop 0
	s_waitcnt lgkmcnt(14)
	s_nop 0
	s_waitcnt lgkmcnt(14)
	s_nop 0
	s_waitcnt lgkmcnt(14)
	s_nop 2
	s_waitcnt lgkmcnt(12)
	s_nop 2
	s_waitcnt lgkmcnt(10)
	s_nop 2
	s_waitcnt lgkmcnt(8)
	s_nop 2
	s_waitcnt lgkmcnt(6)
	s_nop 2
	s_waitcnt lgkmcnt(4)
	s_nop 2
	s_waitcnt lgkmcnt(2)
	s_nop 2
	s_waitcnt lgkmcnt(0)
	s_nop 13
	v_readlane_b32 s0, v255, 37
	v_readlane_b32 s1, v255, 38
	s_nop 4
	s_nop 15
	s_nop 15
	s_nop 14
	v_lshlrev_b32_e32 v64, 16, v44
	v_and_b32_e32 v65, 0xffff0000, v44
	v_and_b32_e32 v67, 0xffff0000, v45
	v_lshlrev_b32_e32 v68, 16, v46
	v_and_b32_e32 v69, 0xffff0000, v46
	v_lshlrev_b32_e32 v70, 16, v47
	v_and_b32_e32 v71, 0xffff0000, v47
	s_waitcnt lgkmcnt(2)
	s_nop 0
	s_waitcnt lgkmcnt(0)
	s_nop 4
	v_mov_b32_e32 v48, v148
	v_max_f32_e64 v126, -v48, 0
	v_mul_f32_e64 v48, |v48|, s93
	v_exp_f32_e32 v48, v48
	s_nop 0
	v_add_f32_e32 v48, 1.0, v48
	s_nop 0
	s_nop 1
	s_nop 0
	s_nop 0
	v_log_f32_e32 v48, v48
	s_nop 0
	v_mul_f32_e32 v130, 0x3f317217, v48
	v_fma_f32 v130, v48, s94, -v130
	v_fmac_f32_e32 v130, 0x3377d1cf, v48
	v_fmac_f32_e32 v130, 0x3f317217, v48
	v_cmp_lt_f32_e64 s[0:1], |v48|, s95
	s_nop 1
	v_cndmask_b32_e64 v48, v48, v130, s[0:1]
	s_nop 0
	s_nop 0
	v_add_f32_e32 v48, v126, v48
	v_mul_f32_e32 v126, 0xbd800000, v48
	v_mov_b32_e32 v130, v49
	s_nop 1
	v_mov_b32_dpp v130, v126 row_shr:1 row_mask:0xf bank_mask:0xf
	v_fmac_f32_e32 v130, 0xbd800000, v48
	s_nop 1
	v_add_f32_dpp v126, v130, v130 row_shr:2 row_mask:0xf bank_mask:0xf bound_ctrl:1
	v_mov_b32_e32 v130, v49
	s_nop 0
	v_add_f32_dpp v126, v126, v126 row_shr:4 row_mask:0xf bank_mask:0xf bound_ctrl:1
	s_nop 1
	v_add_f32_dpp v126, v126, v126 row_shr:8 row_mask:0xf bank_mask:0xf bound_ctrl:1
	s_nop 1
	v_mov_b32_dpp v130, v126 row_bcast:15 row_mask:0xa bank_mask:0xf
	v_add_f32_e32 v126, v126, v130
	v_mov_b32_e32 v130, v49
	s_nop 1
	v_mov_b32_dpp v130, v126 row_bcast:31 row_mask:0xc bank_mask:0xf
	v_add_f32_e32 v126, v126, v130
	s_nop 0
	v_readlane_b32 s4, v126, 63
	s_nop 1
	v_sub_f32_e32 v130, s4, v126
	v_fmac_f32_e32 v126, 0x3d800000, v48
	v_cndmask_b32_e64 v48, v126, v130, s[8:9]
	s_nop 15
	s_nop 3
	v_mov_b32_e32 v126, v149
	v_max_f32_e64 v127, -v126, 0
	v_mul_f32_e64 v126, |v126|, s93
	v_exp_f32_e32 v126, v126
	v_mul_f32_e32 v48, 0x3fb8aa3b, v48
	v_exp_f32_e32 v48, v48
	v_add_f32_e32 v126, 1.0, v126
	s_nop 0
	s_nop 1
	s_nop 0
	s_nop 0
	v_log_f32_e32 v126, v126
	s_nop 0
	v_mul_f32_e32 v130, 0x3f317217, v126
	v_fma_f32 v130, v126, s94, -v130
	v_fmac_f32_e32 v130, 0x3377d1cf, v126
	v_fmac_f32_e32 v130, 0x3f317217, v126
	v_cmp_lt_f32_e64 s[0:1], |v126|, s95
	s_nop 1
	v_cndmask_b32_e64 v126, v126, v130, s[0:1]
	s_nop 0
	s_nop 0
	v_add_f32_e32 v126, v127, v126
	v_mul_f32_e32 v127, 0xbd800000, v126
	v_mov_b32_e32 v130, v49
	s_nop 1
	v_mov_b32_dpp v130, v127 row_shr:1 row_mask:0xf bank_mask:0xf
	v_fmac_f32_e32 v130, 0xbd800000, v126
	s_nop 1
	v_add_f32_dpp v127, v130, v130 row_shr:2 row_mask:0xf bank_mask:0xf bound_ctrl:1
	v_mov_b32_e32 v130, v49
	s_nop 0
	v_add_f32_dpp v127, v127, v127 row_shr:4 row_mask:0xf bank_mask:0xf bound_ctrl:1
	s_nop 1
	v_add_f32_dpp v127, v127, v127 row_shr:8 row_mask:0xf bank_mask:0xf bound_ctrl:1
	s_nop 1
	v_mov_b32_dpp v130, v127 row_bcast:15 row_mask:0xa bank_mask:0xf
	v_add_f32_e32 v127, v127, v130
	v_mov_b32_e32 v130, v49
	s_nop 1
	v_mov_b32_dpp v130, v127 row_bcast:31 row_mask:0xc bank_mask:0xf
	v_add_f32_e32 v127, v127, v130
	s_nop 0
	v_readlane_b32 s5, v127, 63
	s_nop 1
	v_sub_f32_e32 v130, s5, v127
	v_fmac_f32_e32 v127, 0x3d800000, v126
	v_cndmask_b32_e64 v126, v127, v130, s[8:9]
	s_nop 13
	s_nop 0
	s_nop 7
	v_mov_b32_e32 v127, v150
	v_max_f32_e64 v128, -v127, 0
	v_mul_f32_e64 v127, |v127|, s93
	v_exp_f32_e32 v127, v127
	s_nop 0
	v_add_f32_e32 v127, 1.0, v127
	s_nop 0
	s_nop 1
	s_nop 0
	s_nop 0
	v_log_f32_e32 v127, v127
	s_nop 0
	v_mul_f32_e32 v130, 0x3f317217, v127
	v_fma_f32 v130, v127, s94, -v130
	v_fmac_f32_e32 v130, 0x3377d1cf, v127
	v_fmac_f32_e32 v130, 0x3f317217, v127
	v_cmp_lt_f32_e64 s[0:1], |v127|, s95
	s_nop 1
	v_cndmask_b32_e64 v127, v127, v130, s[0:1]
	s_nop 0
	s_nop 0
	v_add_f32_e32 v127, v128, v127
	v_mul_f32_e32 v128, 0xbd800000, v127
	v_mov_b32_e32 v130, v49
	s_nop 1
	v_mov_b32_dpp v130, v128 row_shr:1 row_mask:0xf bank_mask:0xf
	v_fmac_f32_e32 v130, 0xbd800000, v127
	s_nop 1
	v_add_f32_dpp v128, v130, v130 row_shr:2 row_mask:0xf bank_mask:0xf bound_ctrl:1
	v_mov_b32_e32 v130, v49
	s_nop 0
	v_add_f32_dpp v128, v128, v128 row_shr:4 row_mask:0xf bank_mask:0xf bound_ctrl:1
	s_nop 1
	v_add_f32_dpp v128, v128, v128 row_shr:8 row_mask:0xf bank_mask:0xf bound_ctrl:1
	s_nop 1
	v_mov_b32_dpp v130, v128 row_bcast:15 row_mask:0xa bank_mask:0xf
	v_add_f32_e32 v128, v128, v130
	v_mov_b32_e32 v130, v49
	s_nop 1
	v_mov_b32_dpp v130, v128 row_bcast:31 row_mask:0xc bank_mask:0xf
	v_add_f32_e32 v128, v128, v130
	s_nop 0
	v_readlane_b32 s6, v128, 63
	s_nop 1
	v_sub_f32_e32 v130, s6, v128
	v_fmac_f32_e32 v128, 0x3d800000, v127
	v_cndmask_b32_e64 v127, v128, v130, s[8:9]
	s_nop 0
	s_nop 0
	s_nop 2
	s_nop 0
	s_nop 1
	v_mov_b32_e32 v128, v151
	v_max_f32_e64 v129, -v128, 0
	v_mul_f32_e64 v128, |v128|, s93
	v_exp_f32_e32 v128, v128
	s_nop 0
	v_add_f32_e32 v128, 1.0, v128
	s_nop 0
	s_nop 1
	s_nop 0
	s_nop 0
	v_log_f32_e32 v128, v128
	s_nop 0
	v_mul_f32_e32 v130, 0x3f317217, v128
	v_fma_f32 v130, v128, s94, -v130
	v_fmac_f32_e32 v130, 0x3377d1cf, v128
	v_fmac_f32_e32 v130, 0x3f317217, v128
	v_cmp_lt_f32_e64 s[0:1], |v128|, s95
	s_nop 1
	v_cndmask_b32_e64 v128, v128, v130, s[0:1]
	s_nop 0
	s_nop 0
	v_add_f32_e32 v128, v129, v128
	v_mul_f32_e32 v129, 0xbd800000, v128
	v_mov_b32_e32 v130, v49
	s_nop 1
	v_mov_b32_dpp v130, v129 row_shr:1 row_mask:0xf bank_mask:0xf
	v_fmac_f32_e32 v130, 0xbd800000, v128
	s_nop 1
	v_add_f32_dpp v129, v130, v130 row_shr:2 row_mask:0xf bank_mask:0xf bound_ctrl:1
	v_mov_b32_e32 v130, v49
	s_nop 0
	v_add_f32_dpp v129, v129, v129 row_shr:4 row_mask:0xf bank_mask:0xf bound_ctrl:1
	s_nop 1
	v_add_f32_dpp v129, v129, v129 row_shr:8 row_mask:0xf bank_mask:0xf bound_ctrl:1
	s_nop 1
	v_mov_b32_dpp v130, v129 row_bcast:15 row_mask:0xa bank_mask:0xf
	v_add_f32_e32 v129, v129, v130
	v_mov_b32_e32 v130, v49
	s_nop 1
	v_mov_b32_dpp v130, v129 row_bcast:31 row_mask:0xc bank_mask:0xf
	v_add_f32_e32 v129, v129, v130
	s_nop 0
	v_readlane_b32 s7, v129, 63
	s_nop 1
	v_sub_f32_e32 v130, s7, v129
	v_fmac_f32_e32 v129, 0x3d800000, v128
	v_cndmask_b32_e64 v130, v129, v130, s[8:9]
	s_nop 11
	v_mov_b32_e32 v58, v152
	v_max_f32_e64 v62, -v58, 0
	v_mul_f32_e64 v58, |v58|, s93
	v_exp_f32_e32 v58, v58
	s_nop 0
	v_add_f32_e32 v58, 1.0, v58
	s_nop 0
	s_nop 1
	s_nop 0
	s_nop 0
	v_log_f32_e32 v58, v58
	s_nop 0
	v_mul_f32_e32 v66, 0x3f317217, v58
	v_fma_f32 v66, v58, s94, -v66
	v_fmac_f32_e32 v66, 0x3377d1cf, v58
	v_fmac_f32_e32 v66, 0x3f317217, v58
	v_cmp_lt_f32_e64 s[0:1], |v58|, s95
	s_nop 1
	v_cndmask_b32_e64 v58, v58, v66, s[0:1]
	s_nop 0
	s_nop 0
	v_add_f32_e32 v58, v62, v58
	v_mul_f32_e32 v62, 0xbd800000, v58
	v_mov_b32_e32 v66, v49
	s_nop 1
	v_mov_b32_dpp v66, v62 row_shr:1 row_mask:0xf bank_mask:0xf
	v_fmac_f32_e32 v66, 0xbd800000, v58
	s_nop 1
	v_add_f32_dpp v62, v66, v66 row_shr:2 row_mask:0xf bank_mask:0xf bound_ctrl:1
	v_mov_b32_e32 v66, v49
	s_nop 0
	v_add_f32_dpp v62, v62, v62 row_shr:4 row_mask:0xf bank_mask:0xf bound_ctrl:1
	s_nop 1
	v_add_f32_dpp v62, v62, v62 row_shr:8 row_mask:0xf bank_mask:0xf bound_ctrl:1
	s_nop 1
	v_mov_b32_dpp v66, v62 row_bcast:15 row_mask:0xa bank_mask:0xf
	v_add_f32_e32 v62, v62, v66
	v_mov_b32_e32 v66, v49
	s_nop 1
	v_mov_b32_dpp v66, v62 row_bcast:31 row_mask:0xc bank_mask:0xf
	v_add_f32_e32 v62, v62, v66
	s_nop 0
	v_readlane_b32 s91, v62, 63
	s_nop 1
	v_sub_f32_e32 v66, s91, v62
	v_fmac_f32_e32 v62, 0x3d800000, v58
	s_nop 0
	v_cndmask_b32_e64 v62, v62, v66, s[8:9]
	s_nop 2
	v_lshlrev_b32_e32 v66, 16, v45
	s_nop 1
	v_mov_b32_e32 v58, v153
	v_max_f32_e64 v59, -v58, 0
	v_mul_f32_e64 v58, |v58|, s93
	v_exp_f32_e32 v58, v58
	s_nop 0
	v_add_f32_e32 v58, 1.0, v58
	s_nop 0
	s_nop 1
	s_nop 0
	s_nop 0
	v_log_f32_e32 v58, v58
	s_nop 0
	v_mul_f32_e32 v63, 0x3f317217, v58
	v_fma_f32 v63, v58, s94, -v63
	v_fmac_f32_e32 v63, 0x3377d1cf, v58
	v_fmac_f32_e32 v63, 0x3f317217, v58
	v_cmp_lt_f32_e64 s[0:1], |v58|, s95
	s_nop 1
	v_cndmask_b32_e64 v58, v58, v63, s[0:1]
	s_nop 0
	s_nop 0
	v_add_f32_e32 v58, v59, v58
	v_mul_f32_e32 v59, 0xbd800000, v58
	v_mov_b32_e32 v63, v49
	s_nop 1
	v_mov_b32_dpp v63, v59 row_shr:1 row_mask:0xf bank_mask:0xf
	v_fmac_f32_e32 v63, 0xbd800000, v58
	s_nop 1
	v_add_f32_dpp v59, v63, v63 row_shr:2 row_mask:0xf bank_mask:0xf bound_ctrl:1
	v_mov_b32_e32 v63, v49
	s_nop 0
	v_add_f32_dpp v59, v59, v59 row_shr:4 row_mask:0xf bank_mask:0xf bound_ctrl:1
	s_nop 1
	v_add_f32_dpp v59, v59, v59 row_shr:8 row_mask:0xf bank_mask:0xf bound_ctrl:1
	s_nop 1
	v_mov_b32_dpp v63, v59 row_bcast:15 row_mask:0xa bank_mask:0xf
	v_add_f32_e32 v59, v59, v63
	v_mov_b32_e32 v63, v49
	s_nop 1
	v_mov_b32_dpp v63, v59 row_bcast:31 row_mask:0xc bank_mask:0xf
	v_add_f32_e32 v59, v59, v63
	s_nop 0
	v_readlane_b32 s20, v59, 63
	s_nop 1
	v_sub_f32_e32 v63, s20, v59
	v_fmac_f32_e32 v59, 0x3d800000, v58
	v_cndmask_b32_e64 v63, v59, v63, s[8:9]
	s_nop 11
	v_mov_b32_e32 v58, v154
	v_max_f32_e64 v59, -v58, 0
	v_mul_f32_e64 v58, |v58|, s93
	v_exp_f32_e32 v58, v58
	s_nop 0
	v_add_f32_e32 v58, 1.0, v58
	s_nop 0
	s_nop 1
	s_nop 0
	s_nop 0
	v_log_f32_e32 v58, v58
	s_nop 0
	v_mul_f32_e32 v60, 0x3f317217, v58
	v_fma_f32 v60, v58, s94, -v60
	v_fmac_f32_e32 v60, 0x3377d1cf, v58
	v_fmac_f32_e32 v60, 0x3f317217, v58
	v_cmp_lt_f32_e64 s[0:1], |v58|, s95
	s_nop 1
	v_cndmask_b32_e64 v58, v58, v60, s[0:1]
	s_nop 0
	s_nop 0
	v_add_f32_e32 v58, v59, v58
	v_mul_f32_e32 v59, 0xbd800000, v58
	v_mov_b32_e32 v60, v49
	s_nop 1
	v_mov_b32_dpp v60, v59 row_shr:1 row_mask:0xf bank_mask:0xf
	v_fmac_f32_e32 v60, 0xbd800000, v58
	s_nop 1
	v_add_f32_dpp v59, v60, v60 row_shr:2 row_mask:0xf bank_mask:0xf bound_ctrl:1
	v_mov_b32_e32 v60, v49
	s_nop 0
	v_add_f32_dpp v59, v59, v59 row_shr:4 row_mask:0xf bank_mask:0xf bound_ctrl:1
	s_nop 1
	v_add_f32_dpp v59, v59, v59 row_shr:8 row_mask:0xf bank_mask:0xf bound_ctrl:1
	s_nop 1
	v_mov_b32_dpp v60, v59 row_bcast:15 row_mask:0xa bank_mask:0xf
	v_add_f32_e32 v59, v59, v60
	v_mov_b32_e32 v60, v49
	s_nop 1
	v_mov_b32_dpp v60, v59 row_bcast:31 row_mask:0xc bank_mask:0xf
	v_add_f32_e32 v59, v59, v60
	s_nop 0
	v_readlane_b32 s21, v59, 63
	s_nop 1
	v_sub_f32_e32 v60, s21, v59
	v_fmac_f32_e32 v59, 0x3d800000, v58
	v_cndmask_b32_e64 v60, v59, v60, s[8:9]
	s_nop 0
	s_nop 0
	s_nop 2
	s_nop 0
	s_nop 1
	v_mov_b32_e32 v58, v155
	v_max_f32_e64 v59, -v58, 0
	v_mul_f32_e64 v58, |v58|, s93
	v_exp_f32_e32 v58, v58
	s_nop 0
	v_add_f32_e32 v58, 1.0, v58
	s_nop 0
	s_nop 1
	s_nop 0
	s_nop 0
	v_log_f32_e32 v58, v58
	s_nop 0
	v_mul_f32_e32 v61, 0x3f317217, v58
	v_fma_f32 v61, v58, s94, -v61
	v_fmac_f32_e32 v61, 0x3377d1cf, v58
	v_fmac_f32_e32 v61, 0x3f317217, v58
	v_cmp_lt_f32_e64 s[0:1], |v58|, s95
	s_nop 1
	v_cndmask_b32_e64 v58, v58, v61, s[0:1]
	s_nop 0
	s_nop 0
	v_add_f32_e32 v58, v59, v58
	v_mul_f32_e32 v59, 0xbd800000, v58
	v_mov_b32_e32 v61, v49
	v_readlane_b32 s0, v254, 6
	s_add_u32 s0, s90, s0
	v_mov_b32_dpp v61, v59 row_shr:1 row_mask:0xf bank_mask:0xf
	v_fmac_f32_e32 v61, 0xbd800000, v58
	v_readlane_b32 s1, v254, 8
	s_addc_u32 s1, s15, s1
	v_add_f32_dpp v59, v61, v61 row_shr:2 row_mask:0xf bank_mask:0xf bound_ctrl:1
	v_mov_b32_e32 v61, v49
	s_lshl_b64 s[0:1], s[0:1], 10
	v_add_f32_dpp v59, v59, v59 row_shr:4 row_mask:0xf bank_mask:0xf bound_ctrl:1
	s_nop 1
	v_add_f32_dpp v59, v59, v59 row_shr:8 row_mask:0xf bank_mask:0xf bound_ctrl:1
	s_nop 1
	v_mov_b32_dpp v61, v59 row_bcast:15 row_mask:0xa bank_mask:0xf
	v_add_f32_e32 v59, v59, v61
	v_mov_b32_e32 v61, v49
	s_nop 1
	v_mov_b32_dpp v61, v59 row_bcast:31 row_mask:0xc bank_mask:0xf
	v_add_f32_e32 v59, v59, v61
	s_nop 0
	v_readlane_b32 s18, v59, 63
	s_nop 1
	v_sub_f32_e32 v61, s18, v59
	v_fmac_f32_e32 v59, 0x3d800000, v58
	v_cndmask_b32_e64 v58, v59, v61, s[8:9]
	v_mul_f32_e32 v59, 0x3fb8aa3b, v126
	v_exp_f32_e32 v72, v59
	v_mul_f32_e32 v59, 0x3fb8aa3b, v127
	v_mul_f32_e32 v58, 0x3fb8aa3b, v58
	v_exp_f32_e32 v73, v59
	v_exp_f32_e32 v78, v58
	v_cvt_pk_bf16_f32 v58, v48, v72
	v_mul_f32_e32 v48, v48, v64
	v_mul_f32_e32 v59, 0x3fb8aa3b, v130
	v_cvt_pk_bf16_f32 v48, v48, s0
	v_exp_f32_e32 v74, v59
	ds_write_b16 v208, v48 offset:58752
	v_mul_f32_e32 v48, v72, v65
	v_mul_f32_e32 v59, 0x3fb8aa3b, v62
	v_cvt_pk_bf16_f32 v48, v48, s0
	v_exp_f32_e32 v75, v59
	ds_write_b16 v208, v48 offset:58896
	v_mul_f32_e32 v48, v73, v66
	v_mul_f32_e32 v59, 0x3fb8aa3b, v63
	v_cvt_pk_bf16_f32 v48, v48, s0
	v_exp_f32_e32 v76, v59
	ds_write_b16 v208, v48 offset:59040
	v_mul_f32_e32 v48, v74, v67
	v_mul_f32_e32 v59, 0x3fb8aa3b, v60
	v_cvt_pk_bf16_f32 v48, v48, s0
	v_exp_f32_e32 v77, v59
	ds_write_b16 v208, v48 offset:59184
	v_mul_f32_e32 v48, v75, v68
	v_cvt_pk_bf16_f32 v48, v48, s0
	ds_write_b16 v208, v48 offset:59328
	v_mul_f32_e32 v48, v76, v69
	v_cvt_pk_bf16_f32 v48, v48, s0
	ds_write_b16 v208, v48 offset:59472
	v_mul_f32_e32 v48, v77, v70
	v_cvt_pk_bf16_f32 v48, v48, s0
	ds_write_b16 v208, v48 offset:59616
	v_mul_f32_e32 v48, v78, v71
	v_cvt_pk_bf16_f32 v59, v73, v74
	v_cvt_pk_bf16_f32 v60, v75, v76
	v_cvt_pk_bf16_f32 v61, v77, v78
	v_lshl_add_u64 v[62:63], v[202:203], 0, s[0:1]
	v_cvt_pk_bf16_f32 v48, v48, s0
	global_store_dwordx4 v[62:63], v[58:61], off
	ds_write_b16 v208, v48 offset:59760
	s_and_saveexec_b64 s[0:1], s[10:11]
	s_cbranch_execz .LBB0_665
	v_mul_f32_e32 v48, s4, v240
	v_exp_f32_e32 v58, v48
	v_mul_f32_e32 v48, s5, v240
	v_exp_f32_e32 v59, v48
	v_mul_f32_e32 v48, s6, v240
	v_exp_f32_e32 v60, v48
	v_mul_f32_e32 v48, s7, v240
	v_exp_f32_e32 v61, v48
	v_mul_f32_e32 v48, s91, v240
	v_exp_f32_e32 v62, v48
	v_mul_f32_e32 v48, s20, v240
	v_exp_f32_e32 v63, v48
	v_mul_f32_e32 v48, s21, v240
	v_exp_f32_e32 v64, v48
	v_mul_f32_e32 v48, s18, v240
	v_exp_f32_e32 v65, v48
	s_add_u32 s4, s16, s88
	s_addc_u32 s5, s17, s89
	global_store_dwordx4 v49, v[58:61], s[4:5] offset:96
	global_store_dwordx4 v49, v[62:65], s[4:5] offset:112
.LBB0_665:
	s_or_b64 exec, exec, s[0:1]
	s_nop 15
	s_nop 0
	v_readlane_b32 s0, v255, 39
	s_nop 1
	s_waitcnt lgkmcnt(8)
	v_readlane_b32 s1, v255, 40
	s_nop 1
	s_nop 2
	s_nop 1
	s_waitcnt lgkmcnt(8)
	v_readlane_b32 s0, v255, 41
	v_readlane_b32 s1, v255, 42
	s_nop 4
	s_nop 3
	s_waitcnt lgkmcnt(8)
	s_nop 3
	s_waitcnt lgkmcnt(8)
	s_nop 3
	s_waitcnt lgkmcnt(8)
	s_nop 1
	s_waitcnt lgkmcnt(14)
	s_nop 0
	s_waitcnt lgkmcnt(14)
	s_nop 0
	s_waitcnt lgkmcnt(14)
	s_nop 0
	s_waitcnt lgkmcnt(14)
	s_nop 0
	s_waitcnt lgkmcnt(14)
	s_nop 1
	s_waitcnt lgkmcnt(14)
	s_nop 1
	s_waitcnt lgkmcnt(14)
	s_nop 0
	s_waitcnt lgkmcnt(14)
	s_nop 2
	s_waitcnt lgkmcnt(12)
	s_nop 0
	s_waitcnt lgkmcnt(10)
	s_nop 0
	s_waitcnt lgkmcnt(8)
	s_nop 0
	s_waitcnt lgkmcnt(6)
	s_nop 0
	s_waitcnt lgkmcnt(2)
	s_nop 0
	s_waitcnt lgkmcnt(0)
	s_nop 15
	s_nop 15
	s_nop 15
	s_nop 15
	s_nop 7
	v_lshlrev_b32_e32 v64, 16, v50
	v_and_b32_e32 v65, 0xffff0000, v50
	v_and_b32_e32 v67, 0xffff0000, v51
	v_lshlrev_b32_e32 v68, 16, v52
	v_and_b32_e32 v69, 0xffff0000, v52
	v_lshlrev_b32_e32 v70, 16, v53
	v_and_b32_e32 v71, 0xffff0000, v53
	s_waitcnt lgkmcnt(2)
	s_nop 0
	s_waitcnt lgkmcnt(0)
	s_nop 4
	v_mov_b32_e32 v48, v156
	v_max_f32_e64 v126, -v48, 0
	v_mul_f32_e64 v48, |v48|, s93
	v_exp_f32_e32 v48, v48
	s_nop 0
	v_add_f32_e32 v48, 1.0, v48
	s_nop 0
	s_nop 1
	s_nop 0
	s_nop 0
	v_log_f32_e32 v48, v48
	s_nop 0
	v_mul_f32_e32 v130, 0x3f317217, v48
	v_fma_f32 v130, v48, s94, -v130
	v_fmac_f32_e32 v130, 0x3377d1cf, v48
	v_fmac_f32_e32 v130, 0x3f317217, v48
	v_cmp_lt_f32_e64 s[0:1], |v48|, s95
	s_nop 1
	v_cndmask_b32_e64 v48, v48, v130, s[0:1]
	s_nop 0
	s_nop 0
	v_add_f32_e32 v48, v126, v48
	v_mul_f32_e32 v126, 0xbd800000, v48
	v_mov_b32_e32 v130, v49
	s_nop 1
	v_mov_b32_dpp v130, v126 row_shr:1 row_mask:0xf bank_mask:0xf
	v_fmac_f32_e32 v130, 0xbd800000, v48
	s_nop 1
	v_add_f32_dpp v126, v130, v130 row_shr:2 row_mask:0xf bank_mask:0xf bound_ctrl:1
	v_mov_b32_e32 v130, v49
	s_nop 0
	v_add_f32_dpp v126, v126, v126 row_shr:4 row_mask:0xf bank_mask:0xf bound_ctrl:1
	s_nop 1
	v_add_f32_dpp v126, v126, v126 row_shr:8 row_mask:0xf bank_mask:0xf bound_ctrl:1
	s_nop 1
	v_mov_b32_dpp v130, v126 row_bcast:15 row_mask:0xa bank_mask:0xf
	v_add_f32_e32 v126, v126, v130
	v_mov_b32_e32 v130, v49
	s_nop 1
	v_mov_b32_dpp v130, v126 row_bcast:31 row_mask:0xc bank_mask:0xf
	v_add_f32_e32 v126, v126, v130
	s_nop 0
	v_readlane_b32 s4, v126, 63
	s_nop 1
	v_sub_f32_e32 v130, s4, v126
	v_fmac_f32_e32 v126, 0x3d800000, v48
	v_cndmask_b32_e64 v48, v126, v130, s[8:9]
	s_nop 15
	s_nop 3
	v_mov_b32_e32 v126, v164
	v_max_f32_e64 v127, -v126, 0
	v_mul_f32_e64 v126, |v126|, s93
	v_exp_f32_e32 v126, v126
	v_mul_f32_e32 v48, 0x3fb8aa3b, v48
	v_exp_f32_e32 v48, v48
	v_add_f32_e32 v126, 1.0, v126
	s_nop 0
	s_nop 1
	s_nop 0
	s_nop 0
	v_log_f32_e32 v126, v126
	s_nop 0
	v_mul_f32_e32 v130, 0x3f317217, v126
	v_fma_f32 v130, v126, s94, -v130
	v_fmac_f32_e32 v130, 0x3377d1cf, v126
	v_fmac_f32_e32 v130, 0x3f317217, v126
	v_cmp_lt_f32_e64 s[0:1], |v126|, s95
	s_nop 1
	v_cndmask_b32_e64 v126, v126, v130, s[0:1]
	s_nop 0
	s_nop 0
	v_add_f32_e32 v126, v127, v126
	v_mul_f32_e32 v127, 0xbd800000, v126
	v_mov_b32_e32 v130, v49
	s_nop 1
	v_mov_b32_dpp v130, v127 row_shr:1 row_mask:0xf bank_mask:0xf
	v_fmac_f32_e32 v130, 0xbd800000, v126
	s_nop 1
	v_add_f32_dpp v127, v130, v130 row_shr:2 row_mask:0xf bank_mask:0xf bound_ctrl:1
	v_mov_b32_e32 v130, v49
	s_nop 0
	v_add_f32_dpp v127, v127, v127 row_shr:4 row_mask:0xf bank_mask:0xf bound_ctrl:1
	s_nop 1
	v_add_f32_dpp v127, v127, v127 row_shr:8 row_mask:0xf bank_mask:0xf bound_ctrl:1
	s_nop 1
	v_mov_b32_dpp v130, v127 row_bcast:15 row_mask:0xa bank_mask:0xf
	v_add_f32_e32 v127, v127, v130
	v_mov_b32_e32 v130, v49
	s_nop 1
	v_mov_b32_dpp v130, v127 row_bcast:31 row_mask:0xc bank_mask:0xf
	v_add_f32_e32 v127, v127, v130
	s_nop 0
	v_readlane_b32 s5, v127, 63
	s_nop 1
	v_sub_f32_e32 v130, s5, v127
	v_fmac_f32_e32 v127, 0x3d800000, v126
	v_cndmask_b32_e64 v126, v127, v130, s[8:9]
	s_nop 13
	s_nop 0
	s_nop 7
	v_mov_b32_e32 v127, v165
	v_max_f32_e64 v128, -v127, 0
	v_mul_f32_e64 v127, |v127|, s93
	v_exp_f32_e32 v127, v127
	s_nop 0
	v_add_f32_e32 v127, 1.0, v127
	s_nop 0
	s_nop 1
	s_nop 0
	s_nop 0
	v_log_f32_e32 v127, v127
	s_nop 0
	v_mul_f32_e32 v130, 0x3f317217, v127
	v_fma_f32 v130, v127, s94, -v130
	v_fmac_f32_e32 v130, 0x3377d1cf, v127
	v_fmac_f32_e32 v130, 0x3f317217, v127
	v_cmp_lt_f32_e64 s[0:1], |v127|, s95
	s_nop 1
	v_cndmask_b32_e64 v127, v127, v130, s[0:1]
	s_nop 0
	s_nop 0
	v_add_f32_e32 v127, v128, v127
	v_mul_f32_e32 v128, 0xbd800000, v127
	v_mov_b32_e32 v130, v49
	s_nop 1
	v_mov_b32_dpp v130, v128 row_shr:1 row_mask:0xf bank_mask:0xf
	v_fmac_f32_e32 v130, 0xbd800000, v127
	s_nop 1
	v_add_f32_dpp v128, v130, v130 row_shr:2 row_mask:0xf bank_mask:0xf bound_ctrl:1
	v_mov_b32_e32 v130, v49
	s_nop 0
	v_add_f32_dpp v128, v128, v128 row_shr:4 row_mask:0xf bank_mask:0xf bound_ctrl:1
	s_nop 1
	v_add_f32_dpp v128, v128, v128 row_shr:8 row_mask:0xf bank_mask:0xf bound_ctrl:1
	s_nop 1
	v_mov_b32_dpp v130, v128 row_bcast:15 row_mask:0xa bank_mask:0xf
	v_add_f32_e32 v128, v128, v130
	v_mov_b32_e32 v130, v49
	s_nop 1
	v_mov_b32_dpp v130, v128 row_bcast:31 row_mask:0xc bank_mask:0xf
	v_add_f32_e32 v128, v128, v130
	s_nop 0
	v_readlane_b32 s6, v128, 63
	s_nop 1
	v_sub_f32_e32 v130, s6, v128
	v_fmac_f32_e32 v128, 0x3d800000, v127
	v_cndmask_b32_e64 v127, v128, v130, s[8:9]
	s_nop 0
	s_nop 0
	s_nop 2
	s_nop 0
	s_nop 1
	v_mov_b32_e32 v128, v166
	v_max_f32_e64 v129, -v128, 0
	v_mul_f32_e64 v128, |v128|, s93
	v_exp_f32_e32 v128, v128
	s_nop 0
	v_add_f32_e32 v128, 1.0, v128
	s_nop 0
	s_nop 1
	s_nop 0
	s_nop 0
	v_log_f32_e32 v128, v128
	s_nop 0
	v_mul_f32_e32 v130, 0x3f317217, v128
	v_fma_f32 v130, v128, s94, -v130
	v_fmac_f32_e32 v130, 0x3377d1cf, v128
	v_fmac_f32_e32 v130, 0x3f317217, v128
	v_cmp_lt_f32_e64 s[0:1], |v128|, s95
	s_nop 1
	v_cndmask_b32_e64 v128, v128, v130, s[0:1]
	s_nop 0
	s_nop 0
	v_add_f32_e32 v128, v129, v128
	v_mul_f32_e32 v129, 0xbd800000, v128
	v_mov_b32_e32 v130, v49
	s_nop 1
	v_mov_b32_dpp v130, v129 row_shr:1 row_mask:0xf bank_mask:0xf
	v_fmac_f32_e32 v130, 0xbd800000, v128
	s_nop 1
	v_add_f32_dpp v129, v130, v130 row_shr:2 row_mask:0xf bank_mask:0xf bound_ctrl:1
	v_mov_b32_e32 v130, v49
	s_nop 0
	v_add_f32_dpp v129, v129, v129 row_shr:4 row_mask:0xf bank_mask:0xf bound_ctrl:1
	s_nop 1
	v_add_f32_dpp v129, v129, v129 row_shr:8 row_mask:0xf bank_mask:0xf bound_ctrl:1
	s_nop 1
	v_mov_b32_dpp v130, v129 row_bcast:15 row_mask:0xa bank_mask:0xf
	v_add_f32_e32 v129, v129, v130
	v_mov_b32_e32 v130, v49
	s_nop 1
	v_mov_b32_dpp v130, v129 row_bcast:31 row_mask:0xc bank_mask:0xf
	v_add_f32_e32 v129, v129, v130
	s_nop 0
	v_readlane_b32 s7, v129, 63
	s_nop 1
	v_sub_f32_e32 v130, s7, v129
	v_fmac_f32_e32 v129, 0x3d800000, v128
	v_cndmask_b32_e64 v130, v129, v130, s[8:9]
	s_nop 11
	v_mov_b32_e32 v58, v167
	v_max_f32_e64 v62, -v58, 0
	v_mul_f32_e64 v58, |v58|, s93
	v_exp_f32_e32 v58, v58
	s_nop 0
	v_add_f32_e32 v58, 1.0, v58
	s_nop 0
	s_nop 1
	s_nop 0
	s_nop 0
	v_log_f32_e32 v58, v58
	s_nop 0
	v_mul_f32_e32 v66, 0x3f317217, v58
	v_fma_f32 v66, v58, s94, -v66
	v_fmac_f32_e32 v66, 0x3377d1cf, v58
	v_fmac_f32_e32 v66, 0x3f317217, v58
	v_cmp_lt_f32_e64 s[0:1], |v58|, s95
	s_nop 1
	v_cndmask_b32_e64 v58, v58, v66, s[0:1]
	s_nop 0
	s_nop 0
	v_add_f32_e32 v58, v62, v58
	v_mul_f32_e32 v62, 0xbd800000, v58
	v_mov_b32_e32 v66, v49
	s_nop 1
	v_mov_b32_dpp v66, v62 row_shr:1 row_mask:0xf bank_mask:0xf
	v_fmac_f32_e32 v66, 0xbd800000, v58
	s_nop 1
	v_add_f32_dpp v62, v66, v66 row_shr:2 row_mask:0xf bank_mask:0xf bound_ctrl:1
	v_mov_b32_e32 v66, v49
	s_nop 0
	v_add_f32_dpp v62, v62, v62 row_shr:4 row_mask:0xf bank_mask:0xf bound_ctrl:1
	s_nop 1
	v_add_f32_dpp v62, v62, v62 row_shr:8 row_mask:0xf bank_mask:0xf bound_ctrl:1
	s_nop 1
	v_mov_b32_dpp v66, v62 row_bcast:15 row_mask:0xa bank_mask:0xf
	v_add_f32_e32 v62, v62, v66
	v_mov_b32_e32 v66, v49
	s_nop 1
	v_mov_b32_dpp v66, v62 row_bcast:31 row_mask:0xc bank_mask:0xf
	v_add_f32_e32 v62, v62, v66
	s_nop 0
	v_readlane_b32 s91, v62, 63
	s_nop 1
	v_sub_f32_e32 v66, s91, v62
	v_fmac_f32_e32 v62, 0x3d800000, v58
	s_nop 0
	v_cndmask_b32_e64 v62, v62, v66, s[8:9]
	s_nop 2
	v_lshlrev_b32_e32 v66, 16, v51
	s_nop 1
	v_mov_b32_e32 v58, v168
	v_max_f32_e64 v59, -v58, 0
	v_mul_f32_e64 v58, |v58|, s93
	v_exp_f32_e32 v58, v58
	s_nop 0
	v_add_f32_e32 v58, 1.0, v58
	s_nop 0
	s_nop 1
	s_nop 0
	s_nop 0
	v_log_f32_e32 v58, v58
	s_nop 0
	v_mul_f32_e32 v63, 0x3f317217, v58
	v_fma_f32 v63, v58, s94, -v63
	v_fmac_f32_e32 v63, 0x3377d1cf, v58
	v_fmac_f32_e32 v63, 0x3f317217, v58
	v_cmp_lt_f32_e64 s[0:1], |v58|, s95
	s_nop 1
	v_cndmask_b32_e64 v58, v58, v63, s[0:1]
	s_nop 0
	s_nop 0
	v_add_f32_e32 v58, v59, v58
	v_mul_f32_e32 v59, 0xbd800000, v58
	v_mov_b32_e32 v63, v49
	s_nop 1
	v_mov_b32_dpp v63, v59 row_shr:1 row_mask:0xf bank_mask:0xf
	v_fmac_f32_e32 v63, 0xbd800000, v58
	s_nop 1
	v_add_f32_dpp v59, v63, v63 row_shr:2 row_mask:0xf bank_mask:0xf bound_ctrl:1
	v_mov_b32_e32 v63, v49
	s_nop 0
	v_add_f32_dpp v59, v59, v59 row_shr:4 row_mask:0xf bank_mask:0xf bound_ctrl:1
	s_nop 1
	v_add_f32_dpp v59, v59, v59 row_shr:8 row_mask:0xf bank_mask:0xf bound_ctrl:1
	s_nop 1
	v_mov_b32_dpp v63, v59 row_bcast:15 row_mask:0xa bank_mask:0xf
	v_add_f32_e32 v59, v59, v63
	v_mov_b32_e32 v63, v49
	s_nop 1
	v_mov_b32_dpp v63, v59 row_bcast:31 row_mask:0xc bank_mask:0xf
	v_add_f32_e32 v59, v59, v63
	s_nop 0
	v_readlane_b32 s20, v59, 63
	s_nop 1
	v_sub_f32_e32 v63, s20, v59
	v_fmac_f32_e32 v59, 0x3d800000, v58
	v_cndmask_b32_e64 v63, v59, v63, s[8:9]
	s_nop 11
	v_mov_b32_e32 v58, v169
	v_max_f32_e64 v59, -v58, 0
	v_mul_f32_e64 v58, |v58|, s93
	v_exp_f32_e32 v58, v58
	s_nop 0
	v_add_f32_e32 v58, 1.0, v58
	s_nop 0
	s_nop 1
	s_nop 0
	s_nop 0
	v_log_f32_e32 v58, v58
	s_nop 0
	v_mul_f32_e32 v60, 0x3f317217, v58
	v_fma_f32 v60, v58, s94, -v60
	v_fmac_f32_e32 v60, 0x3377d1cf, v58
	v_fmac_f32_e32 v60, 0x3f317217, v58
	v_cmp_lt_f32_e64 s[0:1], |v58|, s95
	s_nop 1
	v_cndmask_b32_e64 v58, v58, v60, s[0:1]
	s_nop 0
	s_nop 0
	v_add_f32_e32 v58, v59, v58
	v_mul_f32_e32 v59, 0xbd800000, v58
	v_mov_b32_e32 v60, v49
	s_nop 1
	v_mov_b32_dpp v60, v59 row_shr:1 row_mask:0xf bank_mask:0xf
	v_fmac_f32_e32 v60, 0xbd800000, v58
	s_nop 1
	v_add_f32_dpp v59, v60, v60 row_shr:2 row_mask:0xf bank_mask:0xf bound_ctrl:1
	v_mov_b32_e32 v60, v49
	s_nop 0
	v_add_f32_dpp v59, v59, v59 row_shr:4 row_mask:0xf bank_mask:0xf bound_ctrl:1
	s_nop 1
	v_add_f32_dpp v59, v59, v59 row_shr:8 row_mask:0xf bank_mask:0xf bound_ctrl:1
	s_nop 1
	v_mov_b32_dpp v60, v59 row_bcast:15 row_mask:0xa bank_mask:0xf
	v_add_f32_e32 v59, v59, v60
	v_mov_b32_e32 v60, v49
	s_nop 1
	v_mov_b32_dpp v60, v59 row_bcast:31 row_mask:0xc bank_mask:0xf
	v_add_f32_e32 v59, v59, v60
	s_nop 0
	v_readlane_b32 s21, v59, 63
	s_nop 1
	v_sub_f32_e32 v60, s21, v59
	v_fmac_f32_e32 v59, 0x3d800000, v58
	v_cndmask_b32_e64 v60, v59, v60, s[8:9]
	s_nop 0
	s_nop 0
	s_nop 2
	s_nop 0
	s_nop 1
	v_mov_b32_e32 v58, v170
	v_max_f32_e64 v59, -v58, 0
	v_mul_f32_e64 v58, |v58|, s93
	v_exp_f32_e32 v58, v58
	s_nop 0
	v_add_f32_e32 v58, 1.0, v58
	s_nop 0
	s_nop 1
	s_nop 0
	s_nop 0
	v_log_f32_e32 v58, v58
	s_nop 0
	v_mul_f32_e32 v61, 0x3f317217, v58
	v_fma_f32 v61, v58, s94, -v61
	v_fmac_f32_e32 v61, 0x3377d1cf, v58
	v_fmac_f32_e32 v61, 0x3f317217, v58
	v_cmp_lt_f32_e64 s[0:1], |v58|, s95
	s_nop 1
	v_cndmask_b32_e64 v58, v58, v61, s[0:1]
	s_nop 0
	s_nop 0
	v_add_f32_e32 v58, v59, v58
	v_mul_f32_e32 v59, 0xbd800000, v58
	v_mov_b32_e32 v61, v49
	v_readlane_b32 s0, v254, 10
	s_add_u32 s0, s90, s0
	v_mov_b32_dpp v61, v59 row_shr:1 row_mask:0xf bank_mask:0xf
	v_fmac_f32_e32 v61, 0xbd800000, v58
	v_readlane_b32 s1, v254, 12
	s_addc_u32 s1, s15, s1
	v_add_f32_dpp v59, v61, v61 row_shr:2 row_mask:0xf bank_mask:0xf bound_ctrl:1
	v_mov_b32_e32 v61, v49
	s_lshl_b64 s[0:1], s[0:1], 10
	v_add_f32_dpp v59, v59, v59 row_shr:4 row_mask:0xf bank_mask:0xf bound_ctrl:1
	s_nop 1
	v_add_f32_dpp v59, v59, v59 row_shr:8 row_mask:0xf bank_mask:0xf bound_ctrl:1
	s_nop 1
	v_mov_b32_dpp v61, v59 row_bcast:15 row_mask:0xa bank_mask:0xf
	v_add_f32_e32 v59, v59, v61
	v_mov_b32_e32 v61, v49
	s_nop 1
	v_mov_b32_dpp v61, v59 row_bcast:31 row_mask:0xc bank_mask:0xf
	v_add_f32_e32 v59, v59, v61
	s_nop 0
	v_readlane_b32 s18, v59, 63
	s_nop 1
	v_sub_f32_e32 v61, s18, v59
	v_fmac_f32_e32 v59, 0x3d800000, v58
	v_cndmask_b32_e64 v58, v59, v61, s[8:9]
	v_mul_f32_e32 v59, 0x3fb8aa3b, v126
	v_exp_f32_e32 v72, v59
	v_mul_f32_e32 v59, 0x3fb8aa3b, v127
	v_mul_f32_e32 v58, 0x3fb8aa3b, v58
	v_exp_f32_e32 v73, v59
	v_exp_f32_e32 v78, v58
	v_cvt_pk_bf16_f32 v58, v48, v72
	v_mul_f32_e32 v48, v48, v64
	v_mul_f32_e32 v59, 0x3fb8aa3b, v130
	v_cvt_pk_bf16_f32 v48, v48, s0
	v_exp_f32_e32 v74, v59
	ds_write_b16 v208, v48 offset:59904
	v_mul_f32_e32 v48, v72, v65
	v_mul_f32_e32 v59, 0x3fb8aa3b, v62
	v_cvt_pk_bf16_f32 v48, v48, s0
	v_exp_f32_e32 v75, v59
	ds_write_b16 v208, v48 offset:60048
	v_mul_f32_e32 v48, v73, v66
	v_mul_f32_e32 v59, 0x3fb8aa3b, v63
	v_cvt_pk_bf16_f32 v48, v48, s0
	v_exp_f32_e32 v76, v59
	ds_write_b16 v208, v48 offset:60192
	v_mul_f32_e32 v48, v74, v67
	v_mul_f32_e32 v59, 0x3fb8aa3b, v60
	v_cvt_pk_bf16_f32 v48, v48, s0
	v_exp_f32_e32 v77, v59
	ds_write_b16 v208, v48 offset:60336
	v_mul_f32_e32 v48, v75, v68
	v_cvt_pk_bf16_f32 v48, v48, s0
	ds_write_b16 v208, v48 offset:60480
	v_mul_f32_e32 v48, v76, v69
	v_cvt_pk_bf16_f32 v48, v48, s0
	ds_write_b16 v208, v48 offset:60624
	v_mul_f32_e32 v48, v77, v70
	v_cvt_pk_bf16_f32 v48, v48, s0
	ds_write_b16 v208, v48 offset:60768
	v_mul_f32_e32 v48, v78, v71
	v_cvt_pk_bf16_f32 v59, v73, v74
	v_cvt_pk_bf16_f32 v60, v75, v76
	v_cvt_pk_bf16_f32 v61, v77, v78
	v_lshl_add_u64 v[62:63], v[202:203], 0, s[0:1]
	v_cvt_pk_bf16_f32 v48, v48, s0
	global_store_dwordx4 v[62:63], v[58:61], off
	ds_write_b16 v208, v48 offset:60912
	s_and_saveexec_b64 s[0:1], s[10:11]
	s_cbranch_execz .LBB0_667
	v_mul_f32_e32 v48, s4, v240
	v_exp_f32_e32 v58, v48
	v_mul_f32_e32 v48, s5, v240
	v_exp_f32_e32 v59, v48
	v_mul_f32_e32 v48, s6, v240
	v_exp_f32_e32 v60, v48
	v_mul_f32_e32 v48, s7, v240
	v_exp_f32_e32 v61, v48
	v_mul_f32_e32 v48, s91, v240
	v_exp_f32_e32 v62, v48
	v_mul_f32_e32 v48, s20, v240
	v_exp_f32_e32 v63, v48
	v_mul_f32_e32 v48, s21, v240
	v_exp_f32_e32 v64, v48
	v_mul_f32_e32 v48, s18, v240
	v_exp_f32_e32 v65, v48
	s_add_u32 s4, s16, s88
	s_addc_u32 s5, s17, s89
	global_store_dwordx4 v49, v[58:61], s[4:5] offset:128
	global_store_dwordx4 v49, v[62:65], s[4:5] offset:144
.LBB0_667:
	s_or_b64 exec, exec, s[0:1]
	s_nop 15
	s_nop 2
	s_waitcnt lgkmcnt(8)
	s_nop 3
	s_waitcnt lgkmcnt(8)
	s_nop 3
	s_waitcnt lgkmcnt(8)
	s_nop 3
	s_waitcnt lgkmcnt(8)
	s_nop 3
	s_waitcnt lgkmcnt(8)
	s_nop 1
	s_waitcnt lgkmcnt(14)
	s_nop 0
	s_waitcnt lgkmcnt(14)
	s_nop 0
	s_waitcnt lgkmcnt(14)
	s_nop 0
	s_waitcnt lgkmcnt(14)
	s_nop 0
	s_waitcnt lgkmcnt(14)
	s_nop 0
	s_waitcnt lgkmcnt(14)
	s_nop 0
	s_waitcnt lgkmcnt(14)
	s_nop 0
	s_waitcnt lgkmcnt(14)
	s_nop 0
	s_waitcnt lgkmcnt(12)
	s_nop 0
	s_waitcnt lgkmcnt(10)
	s_nop 0
	s_waitcnt lgkmcnt(8)
	s_nop 0
	s_waitcnt lgkmcnt(6)
	s_nop 0
	s_waitcnt lgkmcnt(2)
	s_nop 0
	s_waitcnt lgkmcnt(0)
	s_nop 15
	s_nop 15
	s_nop 15
	s_nop 15
	s_nop 11
	v_lshlrev_b32_e32 v64, 16, v54
	v_and_b32_e32 v65, 0xffff0000, v54
	v_and_b32_e32 v67, 0xffff0000, v55
	v_lshlrev_b32_e32 v68, 16, v56
	v_and_b32_e32 v69, 0xffff0000, v56
	v_lshlrev_b32_e32 v70, 16, v57
	v_and_b32_e32 v71, 0xffff0000, v57
	s_waitcnt lgkmcnt(2)
	s_nop 0
	s_waitcnt lgkmcnt(0)
	s_nop 4
	v_mov_b32_e32 v48, v171
	v_max_f32_e64 v126, -v48, 0
	v_mul_f32_e64 v48, |v48|, s93
	v_exp_f32_e32 v48, v48
	s_nop 0
	v_add_f32_e32 v48, 1.0, v48
	s_nop 0
	s_nop 1
	s_nop 0
	s_nop 0
	v_log_f32_e32 v48, v48
	s_nop 0
	v_mul_f32_e32 v130, 0x3f317217, v48
	v_fma_f32 v130, v48, s94, -v130
	v_fmac_f32_e32 v130, 0x3377d1cf, v48
	v_fmac_f32_e32 v130, 0x3f317217, v48
	v_cmp_lt_f32_e64 s[0:1], |v48|, s95
	s_nop 1
	v_cndmask_b32_e64 v48, v48, v130, s[0:1]
	s_nop 0
	s_nop 0
	v_add_f32_e32 v48, v126, v48
	v_mul_f32_e32 v126, 0xbd800000, v48
	v_mov_b32_e32 v130, v49
	s_nop 1
	v_mov_b32_dpp v130, v126 row_shr:1 row_mask:0xf bank_mask:0xf
	v_fmac_f32_e32 v130, 0xbd800000, v48
	s_nop 1
	v_add_f32_dpp v126, v130, v130 row_shr:2 row_mask:0xf bank_mask:0xf bound_ctrl:1
	v_mov_b32_e32 v130, v49
	s_nop 0
	v_add_f32_dpp v126, v126, v126 row_shr:4 row_mask:0xf bank_mask:0xf bound_ctrl:1
	s_nop 1
	v_add_f32_dpp v126, v126, v126 row_shr:8 row_mask:0xf bank_mask:0xf bound_ctrl:1
	s_nop 1
	v_mov_b32_dpp v130, v126 row_bcast:15 row_mask:0xa bank_mask:0xf
	v_add_f32_e32 v126, v126, v130
	v_mov_b32_e32 v130, v49
	s_nop 1
	v_mov_b32_dpp v130, v126 row_bcast:31 row_mask:0xc bank_mask:0xf
	v_add_f32_e32 v126, v126, v130
	s_nop 0
	v_readlane_b32 s4, v126, 63
	s_nop 1
	v_sub_f32_e32 v130, s4, v126
	v_fmac_f32_e32 v126, 0x3d800000, v48
	v_cndmask_b32_e64 v48, v126, v130, s[8:9]
	s_nop 15
	s_nop 3
	v_mov_b32_e32 v126, v176
	v_max_f32_e64 v127, -v126, 0
	v_mul_f32_e64 v126, |v126|, s93
	v_exp_f32_e32 v126, v126
	v_mul_f32_e32 v48, 0x3fb8aa3b, v48
	v_exp_f32_e32 v48, v48
	v_add_f32_e32 v126, 1.0, v126
	s_nop 0
	s_nop 1
	s_nop 0
	s_nop 0
	v_log_f32_e32 v126, v126
	s_nop 0
	v_mul_f32_e32 v130, 0x3f317217, v126
	v_fma_f32 v130, v126, s94, -v130
	v_fmac_f32_e32 v130, 0x3377d1cf, v126
	v_fmac_f32_e32 v130, 0x3f317217, v126
	v_cmp_lt_f32_e64 s[0:1], |v126|, s95
	s_nop 1
	v_cndmask_b32_e64 v126, v126, v130, s[0:1]
	s_nop 0
	s_nop 0
	v_add_f32_e32 v126, v127, v126
	v_mul_f32_e32 v127, 0xbd800000, v126
	v_mov_b32_e32 v130, v49
	s_nop 1
	v_mov_b32_dpp v130, v127 row_shr:1 row_mask:0xf bank_mask:0xf
	v_fmac_f32_e32 v130, 0xbd800000, v126
	s_nop 1
	v_add_f32_dpp v127, v130, v130 row_shr:2 row_mask:0xf bank_mask:0xf bound_ctrl:1
	v_mov_b32_e32 v130, v49
	s_nop 0
	v_add_f32_dpp v127, v127, v127 row_shr:4 row_mask:0xf bank_mask:0xf bound_ctrl:1
	s_nop 1
	v_add_f32_dpp v127, v127, v127 row_shr:8 row_mask:0xf bank_mask:0xf bound_ctrl:1
	s_nop 1
	v_mov_b32_dpp v130, v127 row_bcast:15 row_mask:0xa bank_mask:0xf
	v_add_f32_e32 v127, v127, v130
	v_mov_b32_e32 v130, v49
	s_nop 1
	v_mov_b32_dpp v130, v127 row_bcast:31 row_mask:0xc bank_mask:0xf
	v_add_f32_e32 v127, v127, v130
	s_nop 0
	v_readlane_b32 s5, v127, 63
	s_nop 1
	v_sub_f32_e32 v130, s5, v127
	v_fmac_f32_e32 v127, 0x3d800000, v126
	v_cndmask_b32_e64 v126, v127, v130, s[8:9]
	s_nop 13
	s_nop 0
	s_nop 7
	v_mov_b32_e32 v127, v177
	v_max_f32_e64 v128, -v127, 0
	v_mul_f32_e64 v127, |v127|, s93
	v_exp_f32_e32 v127, v127
	s_nop 0
	v_add_f32_e32 v127, 1.0, v127
	s_nop 0
	s_nop 1
	s_nop 0
	s_nop 0
	v_log_f32_e32 v127, v127
	s_nop 0
	v_mul_f32_e32 v130, 0x3f317217, v127
	v_fma_f32 v130, v127, s94, -v130
	v_fmac_f32_e32 v130, 0x3377d1cf, v127
	v_fmac_f32_e32 v130, 0x3f317217, v127
	v_cmp_lt_f32_e64 s[0:1], |v127|, s95
	s_nop 1
	v_cndmask_b32_e64 v127, v127, v130, s[0:1]
	s_nop 0
	s_nop 0
	v_add_f32_e32 v127, v128, v127
	v_mul_f32_e32 v128, 0xbd800000, v127
	v_mov_b32_e32 v130, v49
	s_nop 1
	v_mov_b32_dpp v130, v128 row_shr:1 row_mask:0xf bank_mask:0xf
	v_fmac_f32_e32 v130, 0xbd800000, v127
	s_nop 1
	v_add_f32_dpp v128, v130, v130 row_shr:2 row_mask:0xf bank_mask:0xf bound_ctrl:1
	v_mov_b32_e32 v130, v49
	s_nop 0
	v_add_f32_dpp v128, v128, v128 row_shr:4 row_mask:0xf bank_mask:0xf bound_ctrl:1
	s_nop 1
	v_add_f32_dpp v128, v128, v128 row_shr:8 row_mask:0xf bank_mask:0xf bound_ctrl:1
	s_nop 1
	v_mov_b32_dpp v130, v128 row_bcast:15 row_mask:0xa bank_mask:0xf
	v_add_f32_e32 v128, v128, v130
	v_mov_b32_e32 v130, v49
	s_nop 1
	v_mov_b32_dpp v130, v128 row_bcast:31 row_mask:0xc bank_mask:0xf
	v_add_f32_e32 v128, v128, v130
	s_nop 0
	v_readlane_b32 s6, v128, 63
	s_nop 1
	v_sub_f32_e32 v130, s6, v128
	v_fmac_f32_e32 v128, 0x3d800000, v127
	v_cndmask_b32_e64 v127, v128, v130, s[8:9]
	s_nop 0
	s_nop 0
	s_nop 2
	s_nop 0
	s_nop 1
	v_mov_b32_e32 v128, v178
	v_max_f32_e64 v129, -v128, 0
	v_mul_f32_e64 v128, |v128|, s93
	v_exp_f32_e32 v128, v128
	s_nop 0
	v_add_f32_e32 v128, 1.0, v128
	s_nop 0
	s_nop 1
	s_nop 0
	s_nop 0
	v_log_f32_e32 v128, v128
	s_nop 0
	v_mul_f32_e32 v130, 0x3f317217, v128
	v_fma_f32 v130, v128, s94, -v130
	v_fmac_f32_e32 v130, 0x3377d1cf, v128
	v_fmac_f32_e32 v130, 0x3f317217, v128
	v_cmp_lt_f32_e64 s[0:1], |v128|, s95
	s_nop 1
	v_cndmask_b32_e64 v128, v128, v130, s[0:1]
	s_nop 0
	s_nop 0
	v_add_f32_e32 v128, v129, v128
	v_mul_f32_e32 v129, 0xbd800000, v128
	v_mov_b32_e32 v130, v49
	s_nop 1
	v_mov_b32_dpp v130, v129 row_shr:1 row_mask:0xf bank_mask:0xf
	v_fmac_f32_e32 v130, 0xbd800000, v128
	s_nop 1
	v_add_f32_dpp v129, v130, v130 row_shr:2 row_mask:0xf bank_mask:0xf bound_ctrl:1
	v_mov_b32_e32 v130, v49
	s_nop 0
	v_add_f32_dpp v129, v129, v129 row_shr:4 row_mask:0xf bank_mask:0xf bound_ctrl:1
	s_nop 1
	v_add_f32_dpp v129, v129, v129 row_shr:8 row_mask:0xf bank_mask:0xf bound_ctrl:1
	s_nop 1
	v_mov_b32_dpp v130, v129 row_bcast:15 row_mask:0xa bank_mask:0xf
	v_add_f32_e32 v129, v129, v130
	v_mov_b32_e32 v130, v49
	s_nop 1
	v_mov_b32_dpp v130, v129 row_bcast:31 row_mask:0xc bank_mask:0xf
	v_add_f32_e32 v129, v129, v130
	s_nop 0
	v_readlane_b32 s7, v129, 63
	s_nop 1
	v_sub_f32_e32 v130, s7, v129
	v_fmac_f32_e32 v129, 0x3d800000, v128
	v_cndmask_b32_e64 v130, v129, v130, s[8:9]
	s_nop 11
	v_mov_b32_e32 v58, v179
	v_max_f32_e64 v62, -v58, 0
	v_mul_f32_e64 v58, |v58|, s93
	v_exp_f32_e32 v58, v58
	s_nop 0
	v_add_f32_e32 v58, 1.0, v58
	s_nop 0
	s_nop 1
	s_nop 0
	s_nop 0
	v_log_f32_e32 v58, v58
	s_nop 0
	v_mul_f32_e32 v66, 0x3f317217, v58
	v_fma_f32 v66, v58, s94, -v66
	v_fmac_f32_e32 v66, 0x3377d1cf, v58
	v_fmac_f32_e32 v66, 0x3f317217, v58
	v_cmp_lt_f32_e64 s[0:1], |v58|, s95
	s_nop 1
	v_cndmask_b32_e64 v58, v58, v66, s[0:1]
	s_nop 0
	s_nop 0
	v_add_f32_e32 v58, v62, v58
	v_mul_f32_e32 v62, 0xbd800000, v58
	v_mov_b32_e32 v66, v49
	s_nop 1
	v_mov_b32_dpp v66, v62 row_shr:1 row_mask:0xf bank_mask:0xf
	v_fmac_f32_e32 v66, 0xbd800000, v58
	s_nop 1
	v_add_f32_dpp v62, v66, v66 row_shr:2 row_mask:0xf bank_mask:0xf bound_ctrl:1
	v_mov_b32_e32 v66, v49
	s_nop 0
	v_add_f32_dpp v62, v62, v62 row_shr:4 row_mask:0xf bank_mask:0xf bound_ctrl:1
	s_nop 1
	v_add_f32_dpp v62, v62, v62 row_shr:8 row_mask:0xf bank_mask:0xf bound_ctrl:1
	s_nop 1
	v_mov_b32_dpp v66, v62 row_bcast:15 row_mask:0xa bank_mask:0xf
	v_add_f32_e32 v62, v62, v66
	v_mov_b32_e32 v66, v49
	s_nop 1
	v_mov_b32_dpp v66, v62 row_bcast:31 row_mask:0xc bank_mask:0xf
	v_add_f32_e32 v62, v62, v66
	s_nop 0
	v_readlane_b32 s20, v62, 63
	s_nop 1
	v_sub_f32_e32 v66, s20, v62
	v_fmac_f32_e32 v62, 0x3d800000, v58
	s_nop 0
	v_cndmask_b32_e64 v62, v62, v66, s[8:9]
	s_nop 2
	v_lshlrev_b32_e32 v66, 16, v55
	s_nop 1
	v_mov_b32_e32 v58, v180
	v_max_f32_e64 v59, -v58, 0
	v_mul_f32_e64 v58, |v58|, s93
	v_exp_f32_e32 v58, v58
	s_nop 0
	v_add_f32_e32 v58, 1.0, v58
	s_nop 0
	s_nop 1
	s_nop 0
	s_nop 0
	v_log_f32_e32 v58, v58
	s_nop 0
	v_mul_f32_e32 v63, 0x3f317217, v58
	v_fma_f32 v63, v58, s94, -v63
	v_fmac_f32_e32 v63, 0x3377d1cf, v58
	v_fmac_f32_e32 v63, 0x3f317217, v58
	v_cmp_lt_f32_e64 s[0:1], |v58|, s95
	s_nop 1
	v_cndmask_b32_e64 v58, v58, v63, s[0:1]
	s_nop 0
	s_nop 0
	v_add_f32_e32 v58, v59, v58
	v_mul_f32_e32 v59, 0xbd800000, v58
	v_mov_b32_e32 v63, v49
	s_nop 1
	v_mov_b32_dpp v63, v59 row_shr:1 row_mask:0xf bank_mask:0xf
	v_fmac_f32_e32 v63, 0xbd800000, v58
	s_nop 1
	v_add_f32_dpp v59, v63, v63 row_shr:2 row_mask:0xf bank_mask:0xf bound_ctrl:1
	v_mov_b32_e32 v63, v49
	s_nop 0
	v_add_f32_dpp v59, v59, v59 row_shr:4 row_mask:0xf bank_mask:0xf bound_ctrl:1
	s_nop 1
	v_add_f32_dpp v59, v59, v59 row_shr:8 row_mask:0xf bank_mask:0xf bound_ctrl:1
	s_nop 1
	v_mov_b32_dpp v63, v59 row_bcast:15 row_mask:0xa bank_mask:0xf
	v_add_f32_e32 v59, v59, v63
	v_mov_b32_e32 v63, v49
	s_nop 1
	v_mov_b32_dpp v63, v59 row_bcast:31 row_mask:0xc bank_mask:0xf
	v_add_f32_e32 v59, v59, v63
	s_nop 0
	v_readlane_b32 s21, v59, 63
	s_nop 1
	v_sub_f32_e32 v63, s21, v59
	v_fmac_f32_e32 v59, 0x3d800000, v58
	v_cndmask_b32_e64 v63, v59, v63, s[8:9]
	s_nop 11
	v_mov_b32_e32 v58, v181
	v_max_f32_e64 v59, -v58, 0
	v_mul_f32_e64 v58, |v58|, s93
	v_exp_f32_e32 v58, v58
	s_nop 0
	v_add_f32_e32 v58, 1.0, v58
	s_nop 0
	s_nop 1
	s_nop 0
	s_nop 0
	v_log_f32_e32 v58, v58
	s_nop 0
	v_mul_f32_e32 v60, 0x3f317217, v58
	v_fma_f32 v60, v58, s94, -v60
	v_fmac_f32_e32 v60, 0x3377d1cf, v58
	v_fmac_f32_e32 v60, 0x3f317217, v58
	v_cmp_lt_f32_e64 s[0:1], |v58|, s95
	s_nop 1
	v_cndmask_b32_e64 v58, v58, v60, s[0:1]
	s_nop 0
	s_nop 0
	v_add_f32_e32 v58, v59, v58
	v_mul_f32_e32 v59, 0xbd800000, v58
	v_mov_b32_e32 v60, v49
	s_nop 1
	v_mov_b32_dpp v60, v59 row_shr:1 row_mask:0xf bank_mask:0xf
	v_fmac_f32_e32 v60, 0xbd800000, v58
	s_nop 1
	v_add_f32_dpp v59, v60, v60 row_shr:2 row_mask:0xf bank_mask:0xf bound_ctrl:1
	v_mov_b32_e32 v60, v49
	s_nop 0
	v_add_f32_dpp v59, v59, v59 row_shr:4 row_mask:0xf bank_mask:0xf bound_ctrl:1
	s_nop 1
	v_add_f32_dpp v59, v59, v59 row_shr:8 row_mask:0xf bank_mask:0xf bound_ctrl:1
	s_nop 1
	v_mov_b32_dpp v60, v59 row_bcast:15 row_mask:0xa bank_mask:0xf
	v_add_f32_e32 v59, v59, v60
	v_mov_b32_e32 v60, v49
	s_nop 1
	v_mov_b32_dpp v60, v59 row_bcast:31 row_mask:0xc bank_mask:0xf
	v_add_f32_e32 v59, v59, v60
	s_nop 0
	v_readlane_b32 s18, v59, 63
	s_nop 1
	v_sub_f32_e32 v60, s18, v59
	v_fmac_f32_e32 v59, 0x3d800000, v58
	v_cndmask_b32_e64 v60, v59, v60, s[8:9]
	s_nop 0
	s_nop 0
	s_nop 2
	s_nop 0
	s_nop 1
	v_mov_b32_e32 v58, v184
	v_max_f32_e64 v59, -v58, 0
	v_mul_f32_e64 v58, |v58|, s93
	v_exp_f32_e32 v58, v58
	s_nop 0
	v_add_f32_e32 v58, 1.0, v58
	s_nop 0
	s_nop 1
	s_nop 0
	s_nop 0
	v_log_f32_e32 v58, v58
	s_nop 0
	v_mul_f32_e32 v61, 0x3f317217, v58
	v_fma_f32 v61, v58, s94, -v61
	v_fmac_f32_e32 v61, 0x3377d1cf, v58
	v_fmac_f32_e32 v61, 0x3f317217, v58
	v_cmp_lt_f32_e64 s[0:1], |v58|, s95
	s_nop 1
	v_cndmask_b32_e64 v58, v58, v61, s[0:1]
	s_nop 0
	s_nop 0
	v_add_f32_e32 v58, v59, v58
	v_mul_f32_e32 v59, 0xbd800000, v58
	v_mov_b32_e32 v61, v49
	v_readlane_b32 s0, v254, 14
	s_add_u32 s0, s90, s0
	v_mov_b32_dpp v61, v59 row_shr:1 row_mask:0xf bank_mask:0xf
	v_fmac_f32_e32 v61, 0xbd800000, v58
	v_readlane_b32 s1, v254, 16
	s_addc_u32 s1, s15, s1
	v_add_f32_dpp v59, v61, v61 row_shr:2 row_mask:0xf bank_mask:0xf bound_ctrl:1
	v_mov_b32_e32 v61, v49
	s_lshl_b64 s[0:1], s[0:1], 10
	v_add_f32_dpp v59, v59, v59 row_shr:4 row_mask:0xf bank_mask:0xf bound_ctrl:1
	s_mov_b64 s[90:91], 0
	s_nop 0
	v_add_f32_dpp v59, v59, v59 row_shr:8 row_mask:0xf bank_mask:0xf bound_ctrl:1
	s_nop 1
	v_mov_b32_dpp v61, v59 row_bcast:15 row_mask:0xa bank_mask:0xf
	v_add_f32_e32 v59, v59, v61
	v_mov_b32_e32 v61, v49
	s_nop 1
	v_mov_b32_dpp v61, v59 row_bcast:31 row_mask:0xc bank_mask:0xf
	v_add_f32_e32 v59, v59, v61
	s_nop 0
	v_readlane_b32 s19, v59, 63
	s_nop 1
	v_sub_f32_e32 v61, s19, v59
	v_fmac_f32_e32 v59, 0x3d800000, v58
	v_cndmask_b32_e64 v58, v59, v61, s[8:9]
	v_mul_f32_e32 v59, 0x3fb8aa3b, v126
	v_exp_f32_e32 v72, v59
	v_mul_f32_e32 v59, 0x3fb8aa3b, v127
	v_mul_f32_e32 v58, 0x3fb8aa3b, v58
	v_exp_f32_e32 v73, v59
	v_exp_f32_e32 v78, v58
	v_cvt_pk_bf16_f32 v58, v48, v72
	v_mul_f32_e32 v48, v48, v64
	v_mul_f32_e32 v59, 0x3fb8aa3b, v130
	v_cvt_pk_bf16_f32 v48, v48, s0
	v_exp_f32_e32 v74, v59
	ds_write_b16 v208, v48 offset:61056
	v_mul_f32_e32 v48, v72, v65
	v_mul_f32_e32 v59, 0x3fb8aa3b, v62
	v_cvt_pk_bf16_f32 v48, v48, s0
	v_exp_f32_e32 v75, v59
	ds_write_b16 v208, v48 offset:61200
	v_mul_f32_e32 v48, v73, v66
	v_mul_f32_e32 v59, 0x3fb8aa3b, v63
	v_cvt_pk_bf16_f32 v48, v48, s0
	v_exp_f32_e32 v76, v59
	ds_write_b16 v208, v48 offset:61344
	v_mul_f32_e32 v48, v74, v67
	v_mul_f32_e32 v59, 0x3fb8aa3b, v60
	v_cvt_pk_bf16_f32 v48, v48, s0
	v_exp_f32_e32 v77, v59
	ds_write_b16 v208, v48 offset:61488
	v_mul_f32_e32 v48, v75, v68
	v_cvt_pk_bf16_f32 v48, v48, s0
	ds_write_b16 v208, v48 offset:61632
	v_mul_f32_e32 v48, v76, v69
	v_cvt_pk_bf16_f32 v48, v48, s0
	ds_write_b16 v208, v48 offset:61776
	v_mul_f32_e32 v48, v77, v70
	v_cvt_pk_bf16_f32 v48, v48, s0
	ds_write_b16 v208, v48 offset:61920
	v_mul_f32_e32 v48, v78, v71
	v_cvt_pk_bf16_f32 v59, v73, v74
	v_cvt_pk_bf16_f32 v60, v75, v76
	v_cvt_pk_bf16_f32 v61, v77, v78
	v_lshl_add_u64 v[62:63], v[202:203], 0, s[0:1]
	v_cvt_pk_bf16_f32 v48, v48, s0
	s_mov_b64 s[0:1], 0
	global_store_dwordx4 v[62:63], v[58:61], off
	ds_write_b16 v208, v48 offset:62064
	s_and_saveexec_b64 vcc, s[10:11]
	s_xor_b64 vcc, exec, vcc
	s_cbranch_execz .LBB0_669
	v_mul_f32_e32 v48, s4, v240
	v_exp_f32_e32 v58, v48
	v_mul_f32_e32 v48, s5, v240
	v_exp_f32_e32 v59, v48
	v_mul_f32_e32 v48, s6, v240
	v_exp_f32_e32 v60, v48
	v_mul_f32_e32 v48, s7, v240
	v_exp_f32_e32 v61, v48
	s_add_u32 s28, s16, s88
	s_addc_u32 s29, s17, s89
	v_mul_f32_e32 v48, s20, v240
	global_store_dwordx4 v49, v[58:61], s[28:29] offset:160
	s_mov_b64 s[90:91], exec
	s_nop 0
	v_exp_f32_e32 v58, v48
	v_mul_f32_e32 v48, s21, v240
	v_exp_f32_e32 v59, v48
	v_mul_f32_e32 v48, s18, v240
	v_exp_f32_e32 v60, v48
	v_mul_f32_e32 v48, s19, v240
	global_store_dwordx3 v49, v[58:60], s[28:29] offset:176
	s_nop 1
	v_exp_f32_e32 v58, v48
